# tile-index arithmetic: the 52 float-reciprocal integer divisions by min(128-8g,8) (always 8 for the 128 row tiles of this problem) replaced by shift/mask with identical quotient, remainder and product
# speedup vs baseline: 1.0103x; 1.0009x over previous
; #define S xcd_barrier(bar);
;     __device__ bool next(int i, Unit& u) const {
;         const int ti = i / nsub; u.sub = i - ti * nsub;
;         const long L = (long)ti * G + c; if (L >= nwg) return false;
;         int wgid = (int)L; { const int q = nwg / NXCD, r = nwg % NXCD, xcd = wgid % NXCD, off = wgid / NXCD; wgid = (xcd < r ? xcd * (q + 1) : r * (q + 1) + (xcd - r) * q) + off; }
;         const int nig = WGM * nN, gid = wgid / nig, fm = gid * WGM, gsz = (nM - fm) < WGM ? (nM - fm) : WGM;
;         u.pm = fm + ((wgid % nig) % gsz); u.pn = (wgid % nig) / gsz; return true;
;     }
; template <class Epi, bool ALIGN_EPI, bool ABLK = false>
; __device__ __forceinline__ void gemm_phase(PG8_LAS unsigned char* lds, const Gemm g, const StaticOrder& S, const Epi& E) {
;     ...
;     if constexpr (Epi::RSTD_LDS) {
; #pragma unroll
;         for (int i = 0; i < RS_MAXT; ++i) { Unit t; if (S.next(i, t)) { const float* p = E.ssqp + (size_t)(t.pm * BM + wid * 32 + (lane & 31)) * 16 + (lane >> 5) * 8; rq[i][0] = *(const f32x4*)p; rq[i][1] = *(const f32x4*)(p + 4); } }
;     }
.LBB0_325:
	s_andn2_b64 vcc, exec, s[4:5]
	s_cbranch_vccnz .LBB0_413
	s_add_u32 s6, s96, 0x3500000
	s_addc_u32 s7, s97, 0
	s_ashr_i32 s53, s2, 31
	s_lshr_b32 s4, s53, 29
	s_add_i32 s4, s2, s4
	s_lshr_b32 s30, s33, 6
	s_ashr_i32 s5, s4, 3
	s_and_b32 s4, s4, -8
	s_ashr_i32 s17, s16, 31
	s_lshl_b32 s26, s30, 5
	s_sub_i32 s4, s2, s4
	s_cmp_lt_i32 s4, 0
	s_movk_i32 s9, 0x161
	s_cselect_b32 s11, s9, 0x160
	s_mul_i32 s4, s11, s4
	s_add_i32 s4, s4, s5
	s_mul_hi_i32 s5, s4, 0x2e8ba2e9
	s_lshr_b32 s11, s5, 31
	s_ashr_i32 s5, s5, 5
	s_add_i32 s5, s5, s11
	s_mul_i32 s11, s5, 0xb0
	s_sub_i32 s4, s4, s11
	s_bfe_u32 s11, s4, 0x3001c
	s_add_i32 s11, s4, s11
	s_and_b32 s11, s11, 0xfff8
	s_sub_i32 s4, s4, s11
	s_sext_i32_i16 s4, s4
	s_lshl_b32 s5, s5, 11
	s_lshl_b32 s4, s4, 8
	v_and_or_b32 v91, v0, 31, s26
	s_add_i32 s4, s4, s5
	v_add_u32_e32 v2, s4, v91
	v_and_b32_e32 v98, 32, v0
	v_mov_b32_e32 v99, 0
	v_ashrrev_i32_e32 v3, 31, v2
	v_lshl_add_u64 v[92:93], s[6:7], 0, v[98:99]
	v_lshlrev_b64 v[2:3], 6, v[2:3]
	v_lshl_add_u64 v[6:7], v[92:93], 0, v[2:3]
	global_load_dwordx4 v[2:5], v[6:7], off offset:16
	s_nop 0
	global_load_dwordx4 v[6:9], v[6:7], off
	s_add_u32 s4, s16, s2
	s_addc_u32 s5, s17, s53
	v_mov_b64_e32 v[18:19], 0xaff
	v_cmp_gt_i64_e32 vcc, s[4:5], v[18:19]
	s_cbranch_vccnz .LBB0_328
	s_ashr_i32 s11, s4, 31
	s_lshr_b32 s11, s11, 29
	s_add_i32 s11, s4, s11
	s_ashr_i32 s22, s11, 3
	s_and_b32 s11, s11, -8
	s_sub_i32 s11, s4, s11
	s_cmp_lt_i32 s11, 0
	s_cselect_b32 s9, s9, 0x160
	s_mul_i32 s9, s9, s11
	s_add_i32 s9, s9, s22
	s_mul_hi_i32 s11, s9, 0x2e8ba2e9
	s_lshr_b32 s22, s11, 31
	s_ashr_i32 s11, s11, 5
	s_add_i32 s11, s11, s22
	s_lshl_b32 s22, s11, 3
	s_sub_i32 s23, 0x80, s22
	s_min_i32 s23, s23, 8
	s_mulk_i32 s11, 0xb0
	s_sub_i32 s9, s9, s11
	s_ashr_i32 s11, s9, 31
	s_abs_i32 s9, s9
	s_and_b32 s9, s9, 7
	s_add_i32 s9, s9, s22
	v_lshl_add_u32 v10, s9, 8, v91
	v_ashrrev_i32_e32 v11, 31, v10
	v_lshlrev_b64 v[10:11], 6, v[10:11]
	v_lshl_add_u64 v[14:15], v[92:93], 0, v[10:11]
	global_load_dwordx4 v[10:13], v[14:15], off offset:16
	s_nop 0
	global_load_dwordx4 v[14:17], v[14:15], off
.LBB0_328:
	s_add_u32 s4, s4, s16
	s_addc_u32 s5, s5, s17
	v_cmp_gt_i64_e32 vcc, s[4:5], v[18:19]
	s_cbranch_vccnz .LBB0_330
	s_ashr_i32 s9, s4, 31
	s_lshr_b32 s9, s9, 29
	s_add_i32 s9, s4, s9
	s_ashr_i32 s11, s9, 3
	s_and_b32 s9, s9, -8
	s_sub_i32 s9, s4, s9
	s_cmp_lt_i32 s9, 0
	s_movk_i32 s22, 0x161
	s_cselect_b32 s22, s22, 0x160
	s_mul_i32 s9, s22, s9
	s_add_i32 s9, s9, s11
	s_mul_hi_i32 s11, s9, 0x2e8ba2e9
	s_lshr_b32 s22, s11, 31
	s_ashr_i32 s11, s11, 5
	s_add_i32 s11, s11, s22
	s_lshl_b32 s22, s11, 3
	s_sub_i32 s23, 0x80, s22
	s_min_i32 s23, s23, 8
	s_mulk_i32 s11, 0xb0
	s_sub_i32 s9, s9, s11
	s_ashr_i32 s11, s9, 31
	s_abs_i32 s9, s9
	s_and_b32 s9, s9, 7
	s_add_i32 s9, s9, s22
	v_lshl_add_u32 v18, s9, 8, v91
	v_ashrrev_i32_e32 v19, 31, v18
	v_lshlrev_b64 v[18:19], 6, v[18:19]
	v_lshl_add_u64 v[22:23], v[92:93], 0, v[18:19]
	global_load_dwordx4 v[18:21], v[22:23], off offset:16
	s_nop 0
	global_load_dwordx4 v[22:25], v[22:23], off
.LBB0_330:
	s_add_u32 s4, s4, s16
	s_addc_u32 s5, s5, s17
	v_mov_b64_e32 v[34:35], 0xaff
	v_cmp_gt_i64_e32 vcc, s[4:5], v[34:35]
	s_cbranch_vccnz .LBB0_332
	s_ashr_i32 s9, s4, 31
	s_lshr_b32 s9, s9, 29
	s_add_i32 s9, s4, s9
	s_ashr_i32 s11, s9, 3
	s_and_b32 s9, s9, -8
	s_sub_i32 s9, s4, s9
	s_cmp_lt_i32 s9, 0
	s_movk_i32 s22, 0x161
	s_cselect_b32 s22, s22, 0x160
	s_mul_i32 s9, s22, s9
	s_add_i32 s9, s9, s11
	s_mul_hi_i32 s11, s9, 0x2e8ba2e9
	s_lshr_b32 s22, s11, 31
	s_ashr_i32 s11, s11, 5
	s_add_i32 s11, s11, s22
	s_lshl_b32 s22, s11, 3
	s_sub_i32 s23, 0x80, s22
	s_min_i32 s23, s23, 8
	s_mulk_i32 s11, 0xb0
	s_sub_i32 s9, s9, s11
	s_ashr_i32 s11, s9, 31
	s_abs_i32 s9, s9
	s_and_b32 s9, s9, 7
	s_add_i32 s9, s9, s22
	v_lshl_add_u32 v26, s9, 8, v91
	v_ashrrev_i32_e32 v27, 31, v26
	v_lshlrev_b64 v[26:27], 6, v[26:27]
	v_lshl_add_u64 v[30:31], v[92:93], 0, v[26:27]
	global_load_dwordx4 v[26:29], v[30:31], off offset:16
	s_nop 0
	global_load_dwordx4 v[30:33], v[30:31], off
.LBB0_332:
	s_add_u32 s4, s4, s16
	s_addc_u32 s5, s5, s17
	v_cmp_gt_i64_e32 vcc, s[4:5], v[34:35]
	s_cbranch_vccnz .LBB0_334
	s_ashr_i32 s9, s4, 31
	s_lshr_b32 s9, s9, 29
	s_add_i32 s9, s4, s9
	s_ashr_i32 s11, s9, 3
	s_and_b32 s9, s9, -8
	s_sub_i32 s9, s4, s9
	s_cmp_lt_i32 s9, 0
	s_movk_i32 s22, 0x161
	s_cselect_b32 s22, s22, 0x160
	s_mul_i32 s9, s22, s9
	s_add_i32 s9, s9, s11
	s_mul_hi_i32 s11, s9, 0x2e8ba2e9
	s_lshr_b32 s22, s11, 31
	s_ashr_i32 s11, s11, 5
	s_add_i32 s11, s11, s22
	s_lshl_b32 s22, s11, 3
	s_sub_i32 s23, 0x80, s22
	s_min_i32 s23, s23, 8
	s_mulk_i32 s11, 0xb0
	s_sub_i32 s9, s9, s11
	s_ashr_i32 s11, s9, 31
	s_abs_i32 s9, s9
	s_and_b32 s9, s9, 7
	s_add_i32 s9, s9, s22
	v_lshl_add_u32 v34, s9, 8, v91
	v_ashrrev_i32_e32 v35, 31, v34
	v_lshlrev_b64 v[34:35], 6, v[34:35]
	v_lshl_add_u64 v[38:39], v[92:93], 0, v[34:35]
	global_load_dwordx4 v[34:37], v[38:39], off offset:16
	s_nop 0
	global_load_dwordx4 v[38:41], v[38:39], off
.LBB0_334:
	s_add_u32 s4, s4, s16
	s_addc_u32 s5, s5, s17
	v_mov_b64_e32 v[50:51], 0xaff
	v_cmp_gt_i64_e32 vcc, s[4:5], v[50:51]
	s_cbranch_vccnz .LBB0_336
	s_ashr_i32 s9, s4, 31
	s_lshr_b32 s9, s9, 29
	s_add_i32 s9, s4, s9
	s_ashr_i32 s11, s9, 3
	s_and_b32 s9, s9, -8
	s_sub_i32 s9, s4, s9
	s_cmp_lt_i32 s9, 0
	s_movk_i32 s22, 0x161
	s_cselect_b32 s22, s22, 0x160
	s_mul_i32 s9, s22, s9
	s_add_i32 s9, s9, s11
	s_mul_hi_i32 s11, s9, 0x2e8ba2e9
	s_lshr_b32 s22, s11, 31
	s_ashr_i32 s11, s11, 5
	s_add_i32 s11, s11, s22
	s_lshl_b32 s22, s11, 3
	s_sub_i32 s23, 0x80, s22
	s_min_i32 s23, s23, 8
	s_mulk_i32 s11, 0xb0
	s_sub_i32 s9, s9, s11
	s_ashr_i32 s11, s9, 31
	s_abs_i32 s9, s9
	s_and_b32 s9, s9, 7
	s_add_i32 s9, s9, s22
	v_lshl_add_u32 v42, s9, 8, v91
	v_ashrrev_i32_e32 v43, 31, v42
	v_lshlrev_b64 v[42:43], 6, v[42:43]
	v_lshl_add_u64 v[46:47], v[92:93], 0, v[42:43]
	global_load_dwordx4 v[42:45], v[46:47], off offset:16
	s_nop 0
	global_load_dwordx4 v[46:49], v[46:47], off
; #define S xcd_barrier(bar);
;     __device__ bool next(int i, Unit& u) const {
;         const int ti = i / nsub; u.sub = i - ti * nsub;
;         const long L = (long)ti * G + c; if (L >= nwg) return false;
;         int wgid = (int)L; { const int q = nwg / NXCD, r = nwg % NXCD, xcd = wgid % NXCD, off = wgid / NXCD; wgid = (xcd < r ? xcd * (q + 1) : r * (q + 1) + (xcd - r) * q) + off; }
;         const int nig = WGM * nN, gid = wgid / nig, fm = gid * WGM, gsz = (nM - fm) < WGM ? (nM - fm) : WGM;
;         u.pm = fm + ((wgid % nig) % gsz); u.pn = (wgid % nig) / gsz; return true;
;     }
; template <class Epi, bool ALIGN_EPI, bool ABLK = false>
; __device__ __forceinline__ void gemm_phase(PG8_LAS unsigned char* lds, const Gemm g, const StaticOrder& S, const Epi& E) {
;     ...
;         for (int i = 0; i < RS_MAXT; ++i) { Unit t; if (S.next(i, t)) { const float* p = E.ssqp + (size_t)(t.pm * BM + wid * 32 + (lane & 31)) * 16 + (lane >> 5) * 8; rq[i][0] = *(const f32x4*)p; rq[i][1] = *(const f32x4*)(p + 4); } }
.LBB0_336:
	s_add_u32 s4, s4, s16
	s_addc_u32 s5, s5, s17
	v_cmp_gt_i64_e32 vcc, s[4:5], v[50:51]
	s_cbranch_vccnz .LBB0_338
	s_ashr_i32 s9, s4, 31
	s_lshr_b32 s9, s9, 29
	s_add_i32 s9, s4, s9
	s_ashr_i32 s11, s9, 3
	s_and_b32 s9, s9, -8
	s_sub_i32 s9, s4, s9
	s_cmp_lt_i32 s9, 0
	s_movk_i32 s22, 0x161
	s_cselect_b32 s22, s22, 0x160
	s_mul_i32 s9, s22, s9
	s_add_i32 s9, s9, s11
	s_mul_hi_i32 s11, s9, 0x2e8ba2e9
	s_lshr_b32 s22, s11, 31
	s_ashr_i32 s11, s11, 5
	s_add_i32 s11, s11, s22
	s_lshl_b32 s22, s11, 3
	s_sub_i32 s23, 0x80, s22
	s_min_i32 s23, s23, 8
	s_mulk_i32 s11, 0xb0
	s_sub_i32 s9, s9, s11
	s_ashr_i32 s11, s9, 31
	s_abs_i32 s9, s9
	s_and_b32 s9, s9, 7
	s_add_i32 s9, s9, s22
	v_lshl_add_u32 v50, s9, 8, v91
	v_ashrrev_i32_e32 v51, 31, v50
	v_lshlrev_b64 v[50:51], 6, v[50:51]
	v_lshl_add_u64 v[54:55], v[92:93], 0, v[50:51]
	global_load_dwordx4 v[50:53], v[54:55], off offset:16
	s_nop 0
	global_load_dwordx4 v[54:57], v[54:55], off
.LBB0_338:
	s_add_u32 s4, s4, s16
	s_addc_u32 s5, s5, s17
	v_mov_b64_e32 v[66:67], 0xaff
	v_cmp_gt_i64_e32 vcc, s[4:5], v[66:67]
	s_cbranch_vccnz .LBB0_340
	s_ashr_i32 s9, s4, 31
	s_lshr_b32 s9, s9, 29
	s_add_i32 s9, s4, s9
	s_ashr_i32 s11, s9, 3
	s_and_b32 s9, s9, -8
	s_sub_i32 s9, s4, s9
	s_cmp_lt_i32 s9, 0
	s_movk_i32 s22, 0x161
	s_cselect_b32 s22, s22, 0x160
	s_mul_i32 s9, s22, s9
	s_add_i32 s9, s9, s11
	s_mul_hi_i32 s11, s9, 0x2e8ba2e9
	s_lshr_b32 s22, s11, 31
	s_ashr_i32 s11, s11, 5
	s_add_i32 s11, s11, s22
	s_lshl_b32 s22, s11, 3
	s_sub_i32 s23, 0x80, s22
	s_min_i32 s23, s23, 8
	s_mulk_i32 s11, 0xb0
	s_sub_i32 s9, s9, s11
	s_ashr_i32 s11, s9, 31
	s_abs_i32 s9, s9
	s_and_b32 s9, s9, 7
	s_add_i32 s9, s9, s22
	v_lshl_add_u32 v58, s9, 8, v91
	v_ashrrev_i32_e32 v59, 31, v58
	v_lshlrev_b64 v[58:59], 6, v[58:59]
	v_lshl_add_u64 v[62:63], v[92:93], 0, v[58:59]
	global_load_dwordx4 v[58:61], v[62:63], off offset:16
	s_nop 0
	global_load_dwordx4 v[62:65], v[62:63], off
.LBB0_340:
	s_add_u32 s4, s4, s16
	s_addc_u32 s5, s5, s17
	v_cmp_gt_i64_e32 vcc, s[4:5], v[66:67]
	s_cbranch_vccnz .LBB0_342
	s_ashr_i32 s9, s4, 31
	s_lshr_b32 s9, s9, 29
	s_add_i32 s9, s4, s9
	s_ashr_i32 s11, s9, 3
	s_and_b32 s9, s9, -8
	s_sub_i32 s9, s4, s9
	s_cmp_lt_i32 s9, 0
	s_movk_i32 s22, 0x161
	s_cselect_b32 s22, s22, 0x160
	s_mul_i32 s9, s22, s9
	s_add_i32 s9, s9, s11
	s_mul_hi_i32 s11, s9, 0x2e8ba2e9
	s_lshr_b32 s22, s11, 31
	s_ashr_i32 s11, s11, 5
	s_add_i32 s11, s11, s22
	s_lshl_b32 s22, s11, 3
	s_sub_i32 s23, 0x80, s22
	s_min_i32 s23, s23, 8
	s_mulk_i32 s11, 0xb0
	s_sub_i32 s9, s9, s11
	s_ashr_i32 s11, s9, 31
	s_abs_i32 s9, s9
	s_and_b32 s9, s9, 7
	s_add_i32 s9, s9, s22
	v_lshl_add_u32 v66, s9, 8, v91
	v_ashrrev_i32_e32 v67, 31, v66
	v_lshlrev_b64 v[66:67], 6, v[66:67]
	v_lshl_add_u64 v[70:71], v[92:93], 0, v[66:67]
	global_load_dwordx4 v[66:69], v[70:71], off offset:16
	s_nop 0
	global_load_dwordx4 v[70:73], v[70:71], off
.LBB0_342:
	s_add_u32 s4, s4, s16
	s_addc_u32 s5, s5, s17
	v_mov_b64_e32 v[82:83], 0xaff
	v_cmp_gt_i64_e32 vcc, s[4:5], v[82:83]
	s_cbranch_vccnz .LBB0_344
	s_ashr_i32 s9, s4, 31
	s_lshr_b32 s9, s9, 29
	s_add_i32 s9, s4, s9
	s_ashr_i32 s11, s9, 3
	s_and_b32 s9, s9, -8
	s_sub_i32 s9, s4, s9
	s_cmp_lt_i32 s9, 0
	s_movk_i32 s22, 0x161
	s_cselect_b32 s22, s22, 0x160
	s_mul_i32 s9, s22, s9
	s_add_i32 s9, s9, s11
	s_mul_hi_i32 s11, s9, 0x2e8ba2e9
	s_lshr_b32 s22, s11, 31
	s_ashr_i32 s11, s11, 5
	s_add_i32 s11, s11, s22
	s_lshl_b32 s22, s11, 3
	s_sub_i32 s23, 0x80, s22
	s_min_i32 s23, s23, 8
	s_mulk_i32 s11, 0xb0
	s_sub_i32 s9, s9, s11
	s_ashr_i32 s11, s9, 31
	s_abs_i32 s9, s9
	s_and_b32 s9, s9, 7
	s_add_i32 s9, s9, s22
	v_lshl_add_u32 v74, s9, 8, v91
	v_ashrrev_i32_e32 v75, 31, v74
	v_lshlrev_b64 v[74:75], 6, v[74:75]
	v_lshl_add_u64 v[78:79], v[92:93], 0, v[74:75]
	global_load_dwordx4 v[74:77], v[78:79], off offset:16
	s_nop 0
	global_load_dwordx4 v[78:81], v[78:79], off
.LBB0_344:
	s_add_u32 s4, s4, s16
	s_addc_u32 s5, s5, s17
	v_cmp_gt_i64_e32 vcc, s[4:5], v[82:83]
	s_cbranch_vccnz .LBB0_346
	s_ashr_i32 s9, s4, 31
	s_lshr_b32 s9, s9, 29
	s_add_i32 s9, s4, s9
	s_ashr_i32 s11, s9, 3
	s_and_b32 s9, s9, -8
	s_sub_i32 s9, s4, s9
	s_cmp_lt_i32 s9, 0
	s_movk_i32 s22, 0x161
	s_cselect_b32 s22, s22, 0x160
	s_mul_i32 s9, s22, s9
	s_add_i32 s9, s9, s11
	s_mul_hi_i32 s11, s9, 0x2e8ba2e9
	s_lshr_b32 s22, s11, 31
	s_ashr_i32 s11, s11, 5
	s_add_i32 s11, s11, s22
	s_lshl_b32 s22, s11, 3
	s_sub_i32 s23, 0x80, s22
	s_min_i32 s23, s23, 8
	s_mulk_i32 s11, 0xb0
	s_sub_i32 s9, s9, s11
	s_ashr_i32 s11, s9, 31
	s_abs_i32 s9, s9
	s_and_b32 s9, s9, 7
	s_add_i32 s9, s9, s22
	v_lshl_add_u32 v82, s9, 8, v91
	v_ashrrev_i32_e32 v83, 31, v82
	v_lshlrev_b64 v[82:83], 6, v[82:83]
	v_lshl_add_u64 v[86:87], v[92:93], 0, v[82:83]
	global_load_dwordx4 v[82:85], v[86:87], off offset:16
	s_nop 0
	global_load_dwordx4 v[86:89], v[86:87], off
.LBB0_346:
	s_add_u32 s4, s4, s16
	s_addc_u32 s5, s5, s17
	v_mov_b64_e32 v[94:95], 0xaff
	v_cmp_gt_i64_e32 vcc, s[4:5], v[94:95]
	v_lshrrev_b32_e32 v99, 2, v0
	s_cbranch_vccnz .LBB0_348
	s_ashr_i32 s5, s4, 31
	s_lshr_b32 s5, s5, 29
	s_add_i32 s5, s4, s5
	s_ashr_i32 s9, s5, 3
	s_and_b32 s5, s5, -8
	s_sub_i32 s4, s4, s5
	s_cmp_lt_i32 s4, 0
	s_movk_i32 s5, 0x161
	s_cselect_b32 s5, s5, 0x160
	s_mul_i32 s4, s5, s4
	s_add_i32 s4, s4, s9
	s_mul_hi_i32 s5, s4, 0x2e8ba2e9
	s_lshr_b32 s9, s5, 31
	s_ashr_i32 s5, s5, 5
	s_add_i32 s5, s5, s9
	s_lshl_b32 s9, s5, 3
	s_sub_i32 s11, 0x80, s9
	s_min_i32 s11, s11, 8
	s_mulk_i32 s5, 0xb0
	s_sub_i32 s4, s4, s5
	s_ashr_i32 s5, s4, 31
	s_abs_i32 s4, s4
	s_and_b32 s4, s4, 7
	s_add_i32 s4, s4, s9
	v_lshl_add_u32 v90, s4, 8, v91
	v_ashrrev_i32_e32 v91, 31, v90
	v_lshlrev_b64 v[90:91], 6, v[90:91]
	v_lshl_add_u64 v[94:95], v[92:93], 0, v[90:91]
	global_load_dwordx4 v[90:93], v[94:95], off offset:16
	s_nop 0
	global_load_dwordx4 v[94:97], v[94:95], off

; #define S xcd_barrier(bar);
;     __device__ bool next(int i, Unit& u) const {
;         const int ti = i / nsub; u.sub = i - ti * nsub;
;         const long L = (long)ti * G + c; if (L >= nwg) return false;
;         int wgid = (int)L; { const int q = nwg / NXCD, r = nwg % NXCD, xcd = wgid % NXCD, off = wgid / NXCD; wgid = (xcd < r ? xcd * (q + 1) : r * (q + 1) + (xcd - r) * q) + off; }
;         const int nig = WGM * nN, gid = wgid / nig, fm = gid * WGM, gsz = (nM - fm) < WGM ? (nM - fm) : WGM;
;         u.pm = fm + ((wgid % nig) % gsz); u.pn = (wgid % nig) / gsz; return true;
;     }
; template <class Epi, bool ALIGN_EPI, bool ABLK = false>
; __device__ __forceinline__ void gemm_phase(PG8_LAS unsigned char* lds, const Gemm g, const StaticOrder& S, const Epi& E) {
;     ...
;         const bool has_next = S.next(ui + 1, nxt);
;         const char* nA = has_next ? PG8_ABASE(nxt) : cA; const char* nB = has_next ? PG8_BBASE(nxt) : cB;
.LBB0_399:
	s_add_i32 s33, s60, 1
	s_mul_i32 s5, s33, s16
	s_mul_hi_i32 s4, s33, s16
	s_add_u32 s42, s5, s2
	s_addc_u32 s43, s4, s53
	v_cmp_gt_i64_e64 s[4:5], s[42:43], v[164:165]
	v_cmp_lt_i64_e64 s[6:7], s[42:43], v[162:163]
	s_and_b64 vcc, exec, s[4:5]
	s_cbranch_vccnz .LBB0_401
	s_ashr_i32 s38, s42, 31
	s_lshr_b32 s38, s38, 29
	s_add_i32 s38, s42, s38
	s_ashr_i32 s39, s38, 3
	s_and_b32 s38, s38, -8
	s_sub_i32 s38, s42, s38
	s_cmp_lt_i32 s38, 0
	s_movk_i32 s40, 0x161
	s_cselect_b32 s40, s40, 0x160
	s_mul_i32 s38, s40, s38
	s_add_i32 s38, s38, s39
	s_mul_hi_i32 s39, s38, 0x2e8ba2e9
	s_lshr_b32 s40, s39, 31
	s_ashr_i32 s39, s39, 5
	s_add_i32 s39, s39, s40
	s_lshl_b32 s40, s39, 3
	s_sub_i32 s41, 0x80, s40
	s_min_i32 s41, s41, 8
	s_mulk_i32 s39, 0xb0
	s_sub_i32 s39, s38, s39
	s_abs_i32 s38, s39
	s_ashr_i32 s38, s39, 3
	s_lshl_b32 s41, s38, 3
	s_and_b32 s39, s39, 7
	s_add_i32 s40, s39, s40

; #define S xcd_barrier(bar);
;     __device__ bool next(int i, Unit& u) const {
;         const int ti = i / nsub; u.sub = i - ti * nsub;
;         const long L = (long)ti * G + c; if (L >= nwg) return false;
;         int wgid = (int)L; { const int q = nwg / NXCD, r = nwg % NXCD, xcd = wgid % NXCD, off = wgid / NXCD; wgid = (xcd < r ? xcd * (q + 1) : r * (q + 1) + (xcd - r) * q) + off; }
;         const int nig = WGM * nN, gid = wgid / nig, fm = gid * WGM, gsz = (nM - fm) < WGM ? (nM - fm) : WGM;
;         u.pm = fm + ((wgid % nig) % gsz); u.pn = (wgid % nig) / gsz; return true;
;     }
; template <class Epi, bool ALIGN_EPI, bool ABLK = false>
; __device__ __forceinline__ void gemm_phase(PG8_LAS unsigned char* lds, const Gemm g, const StaticOrder& S, const Epi& E) {
;     ...
;         const bool has_next = S.next(ui + 1, nxt);
;         const char* nA = has_next ? PG8_ABASE(nxt) : cA; const char* nB = has_next ? PG8_BBASE(nxt) : cB;
.LBB0_534:
	s_ashr_i32 s6, s48, 3
	s_add_i32 s6, s54, s6
	s_ashr_i32 s7, s6, 31
	s_lshr_b32 s7, s7, 27
	s_add_i32 s7, s6, s7
	s_ashr_i32 s48, s7, 5
	s_lshl_b32 s48, s48, 3
	s_sub_i32 s49, 0x80, s48
	s_min_i32 s49, s49, 8
	s_andn2_b32 s7, s7, 31
	s_sub_i32 s6, s6, s7
	s_abs_i32 s7, s6
	s_ashr_i32 s76, s6, 3
	s_lshl_b32 s7, s76, 3
	s_and_b32 s6, s6, 7
	s_add_i32 s77, s48, s6

; #define S xcd_barrier(bar);
;     __device__ bool next(int i, Unit& u) const {
;         const int ti = i / nsub; u.sub = i - ti * nsub;
;         const long L = (long)ti * G + c; if (L >= nwg) return false;
;         int wgid = (int)L; { const int q = nwg / NXCD, r = nwg % NXCD, xcd = wgid % NXCD, off = wgid / NXCD; wgid = (xcd < r ? xcd * (q + 1) : r * (q + 1) + (xcd - r) * q) + off; }
;         const int nig = WGM * nN, gid = wgid / nig, fm = gid * WGM, gsz = (nM - fm) < WGM ? (nM - fm) : WGM;
;         u.pm = fm + ((wgid % nig) % gsz); u.pn = (wgid % nig) / gsz; return true;
;     }
; template <class Epi, bool ALIGN_EPI, bool ABLK = false>
; __device__ __forceinline__ void gemm_phase(PG8_LAS unsigned char* lds, const Gemm g, const StaticOrder& S, const Epi& E) {
;     ...
;         for (int i = 0; i < RS_MAXT; ++i) { Unit t; if (S.next(i, t)) { const float* p = E.ssqp + (size_t)(t.pm * BM + wid * 32 + (lane & 31)) * 16 + (lane >> 5) * 8; rq[i][0] = *(const f32x4*)p; rq[i][1] = *(const f32x4*)(p + 4); } }
.LBB0_741:
	s_add_u32 s20, s96, 0x7cc0000
	s_addc_u32 s21, s97, 0
	s_add_u32 s22, s96, 0xbd40000
	s_addc_u32 s23, s97, 0
	s_add_u32 s24, s96, 0xfdc0000
	s_addc_u32 s25, s97, 0
	s_add_u32 s26, s96, 0x17ec0000
	s_addc_u32 s27, s97, 0
	s_add_u32 s80, s96, 0x1df80000
	s_addc_u32 s81, s97, 0
	s_andn2_b64 vcc, exec, s[4:5]
	s_cbranch_vccnz .LBB0_1012
	s_add_u32 s6, s96, 0x3704000
	s_addc_u32 s7, s97, 0
	s_ashr_i32 s19, s2, 31
	s_lshr_b32 s4, s19, 29
	s_add_i32 s4, s2, s4
	s_lshr_b32 s1, s12, 6
	s_ashr_i32 s5, s4, 3
	s_and_b32 s4, s4, -8
	s_lshl_b32 s0, s1, 5
	s_ashr_i32 s17, s16, 31
	s_sub_i32 s4, s2, s4
	s_cmp_lt_i32 s4, 0
	s_movk_i32 s8, 0x121
	s_cselect_b32 s9, s8, 0x120
	s_mul_i32 s4, s9, s4
	s_add_i32 s4, s4, s5
	s_mul_hi_i32 s5, s4, 0x38e38e39
	s_lshr_b32 s9, s5, 31
	s_ashr_i32 s5, s5, 5
	s_add_i32 s5, s5, s9
	s_mul_i32 s9, s5, 0x90
	s_sub_i32 s4, s4, s9
	s_bfe_u32 s9, s4, 0x3001c
	s_add_i32 s9, s4, s9
	s_and_b32 s9, s9, 0xfff8
	s_sub_i32 s4, s4, s9
	s_sext_i32_i16 s4, s4
	s_lshl_b32 s5, s5, 11
	s_lshl_b32 s4, s4, 8
	v_and_or_b32 v91, v0, 31, s0
	s_add_i32 s4, s4, s5
	v_add_u32_e32 v2, s4, v91
	v_and_b32_e32 v98, 32, v0
	v_mov_b32_e32 v99, 0
	v_ashrrev_i32_e32 v3, 31, v2
	v_lshl_add_u64 v[92:93], s[6:7], 0, v[98:99]
	v_lshlrev_b64 v[2:3], 6, v[2:3]
	v_lshl_add_u64 v[6:7], v[92:93], 0, v[2:3]
	global_load_dwordx4 v[2:5], v[6:7], off offset:16
	s_nop 0
	global_load_dwordx4 v[6:9], v[6:7], off
	s_add_u32 s4, s16, s2
	s_addc_u32 s5, s17, s19
	v_mov_b64_e32 v[18:19], 0x8ff
	v_cmp_gt_i64_e32 vcc, s[4:5], v[18:19]
	s_cbranch_vccnz .LBB0_744
	s_ashr_i32 s9, s4, 31
	s_lshr_b32 s9, s9, 29
	s_add_i32 s9, s4, s9
	s_ashr_i32 s10, s9, 3
	s_and_b32 s9, s9, -8
	s_sub_i32 s9, s4, s9
	s_cmp_lt_i32 s9, 0
	s_cselect_b32 s8, s8, 0x120
	s_mul_i32 s8, s8, s9
	s_add_i32 s8, s8, s10
	s_mul_hi_i32 s9, s8, 0x38e38e39
	s_lshr_b32 s10, s9, 31
	s_ashr_i32 s9, s9, 5
	s_add_i32 s9, s9, s10
	s_lshl_b32 s10, s9, 3
	s_sub_i32 s11, 0x80, s10
	s_min_i32 s11, s11, 8
	s_mulk_i32 s9, 0x90
	s_sub_i32 s8, s8, s9
	s_ashr_i32 s9, s8, 31
	s_abs_i32 s8, s8
	s_and_b32 s8, s8, 7
	s_add_i32 s8, s8, s10
	v_lshl_add_u32 v10, s8, 8, v91
	v_ashrrev_i32_e32 v11, 31, v10
	v_lshlrev_b64 v[10:11], 6, v[10:11]
	v_lshl_add_u64 v[14:15], v[92:93], 0, v[10:11]
	global_load_dwordx4 v[10:13], v[14:15], off offset:16
	s_nop 0
	global_load_dwordx4 v[14:17], v[14:15], off
.LBB0_744:
	s_add_u32 s4, s4, s16
	s_addc_u32 s5, s5, s17
	v_cmp_gt_i64_e32 vcc, s[4:5], v[18:19]
	s_cbranch_vccnz .LBB0_746
	s_ashr_i32 s8, s4, 31
	s_lshr_b32 s8, s8, 29
	s_add_i32 s8, s4, s8
	s_ashr_i32 s9, s8, 3
	s_and_b32 s8, s8, -8
	s_sub_i32 s8, s4, s8
	s_cmp_lt_i32 s8, 0
	s_movk_i32 s10, 0x121
	s_cselect_b32 s10, s10, 0x120
	s_mul_i32 s8, s10, s8
	s_add_i32 s8, s8, s9
	s_mul_hi_i32 s9, s8, 0x38e38e39
	s_lshr_b32 s10, s9, 31
	s_ashr_i32 s9, s9, 5
	s_add_i32 s9, s9, s10
	s_lshl_b32 s10, s9, 3
	s_sub_i32 s11, 0x80, s10
	s_min_i32 s11, s11, 8
	s_mulk_i32 s9, 0x90
	s_sub_i32 s8, s8, s9
	s_ashr_i32 s9, s8, 31
	s_abs_i32 s8, s8
	s_and_b32 s8, s8, 7
	s_add_i32 s8, s8, s10
	v_lshl_add_u32 v18, s8, 8, v91
	v_ashrrev_i32_e32 v19, 31, v18
	v_lshlrev_b64 v[18:19], 6, v[18:19]
	v_lshl_add_u64 v[22:23], v[92:93], 0, v[18:19]
	global_load_dwordx4 v[18:21], v[22:23], off offset:16
	s_nop 0
	global_load_dwordx4 v[22:25], v[22:23], off
.LBB0_746:
	s_add_u32 s4, s4, s16
	s_addc_u32 s5, s5, s17
	v_mov_b64_e32 v[34:35], 0x8ff
	v_cmp_gt_i64_e32 vcc, s[4:5], v[34:35]
	s_cbranch_vccnz .LBB0_748
	s_ashr_i32 s8, s4, 31
	s_lshr_b32 s8, s8, 29
	s_add_i32 s8, s4, s8
	s_ashr_i32 s9, s8, 3
	s_and_b32 s8, s8, -8
	s_sub_i32 s8, s4, s8
	s_cmp_lt_i32 s8, 0
	s_movk_i32 s10, 0x121
	s_cselect_b32 s10, s10, 0x120
	s_mul_i32 s8, s10, s8
	s_add_i32 s8, s8, s9
	s_mul_hi_i32 s9, s8, 0x38e38e39
	s_lshr_b32 s10, s9, 31
	s_ashr_i32 s9, s9, 5
	s_add_i32 s9, s9, s10
	s_lshl_b32 s10, s9, 3
	s_sub_i32 s11, 0x80, s10
	s_min_i32 s11, s11, 8
	s_mulk_i32 s9, 0x90
	s_sub_i32 s8, s8, s9
	s_ashr_i32 s9, s8, 31
	s_abs_i32 s8, s8
	s_and_b32 s8, s8, 7
	s_add_i32 s8, s8, s10
	v_lshl_add_u32 v26, s8, 8, v91
	v_ashrrev_i32_e32 v27, 31, v26
	v_lshlrev_b64 v[26:27], 6, v[26:27]
	v_lshl_add_u64 v[30:31], v[92:93], 0, v[26:27]
	global_load_dwordx4 v[26:29], v[30:31], off offset:16
	s_nop 0
	global_load_dwordx4 v[30:33], v[30:31], off
.LBB0_748:
	s_add_u32 s4, s4, s16
	s_addc_u32 s5, s5, s17
	v_cmp_gt_i64_e32 vcc, s[4:5], v[34:35]
	s_cbranch_vccnz .LBB0_750
	s_ashr_i32 s8, s4, 31
	s_lshr_b32 s8, s8, 29
	s_add_i32 s8, s4, s8
	s_ashr_i32 s9, s8, 3
	s_and_b32 s8, s8, -8
	s_sub_i32 s8, s4, s8
	s_cmp_lt_i32 s8, 0
	s_movk_i32 s10, 0x121
	s_cselect_b32 s10, s10, 0x120
	s_mul_i32 s8, s10, s8
	s_add_i32 s8, s8, s9
	s_mul_hi_i32 s9, s8, 0x38e38e39
	s_lshr_b32 s10, s9, 31
	s_ashr_i32 s9, s9, 5
	s_add_i32 s9, s9, s10
	s_lshl_b32 s10, s9, 3
	s_sub_i32 s11, 0x80, s10
	s_min_i32 s11, s11, 8
	s_mulk_i32 s9, 0x90
	s_sub_i32 s8, s8, s9
	s_ashr_i32 s9, s8, 31
	s_abs_i32 s8, s8
	s_and_b32 s8, s8, 7
	s_add_i32 s8, s8, s10
	v_lshl_add_u32 v34, s8, 8, v91
	v_ashrrev_i32_e32 v35, 31, v34
	v_lshlrev_b64 v[34:35], 6, v[34:35]
	v_lshl_add_u64 v[38:39], v[92:93], 0, v[34:35]
	global_load_dwordx4 v[34:37], v[38:39], off offset:16
	s_nop 0
	global_load_dwordx4 v[38:41], v[38:39], off
; #define S xcd_barrier(bar);
;     __device__ bool next(int i, Unit& u) const {
;         const int ti = i / nsub; u.sub = i - ti * nsub;
;         const long L = (long)ti * G + c; if (L >= nwg) return false;
;         int wgid = (int)L; { const int q = nwg / NXCD, r = nwg % NXCD, xcd = wgid % NXCD, off = wgid / NXCD; wgid = (xcd < r ? xcd * (q + 1) : r * (q + 1) + (xcd - r) * q) + off; }
;         const int nig = WGM * nN, gid = wgid / nig, fm = gid * WGM, gsz = (nM - fm) < WGM ? (nM - fm) : WGM;
;         u.pm = fm + ((wgid % nig) % gsz); u.pn = (wgid % nig) / gsz; return true;
;     }
; template <class Epi, bool ALIGN_EPI, bool ABLK = false>
; __device__ __forceinline__ void gemm_phase(PG8_LAS unsigned char* lds, const Gemm g, const StaticOrder& S, const Epi& E) {
;     ...
;         for (int i = 0; i < RS_MAXT; ++i) { Unit t; if (S.next(i, t)) { const float* p = E.ssqp + (size_t)(t.pm * BM + wid * 32 + (lane & 31)) * 16 + (lane >> 5) * 8; rq[i][0] = *(const f32x4*)p; rq[i][1] = *(const f32x4*)(p + 4); } }
.LBB0_750:
	s_add_u32 s4, s4, s16
	s_addc_u32 s5, s5, s17
	v_mov_b64_e32 v[50:51], 0x8ff
	v_cmp_gt_i64_e32 vcc, s[4:5], v[50:51]
	s_cbranch_vccnz .LBB0_752
	s_ashr_i32 s8, s4, 31
	s_lshr_b32 s8, s8, 29
	s_add_i32 s8, s4, s8
	s_ashr_i32 s9, s8, 3
	s_and_b32 s8, s8, -8
	s_sub_i32 s8, s4, s8
	s_cmp_lt_i32 s8, 0
	s_movk_i32 s10, 0x121
	s_cselect_b32 s10, s10, 0x120
	s_mul_i32 s8, s10, s8
	s_add_i32 s8, s8, s9
	s_mul_hi_i32 s9, s8, 0x38e38e39
	s_lshr_b32 s10, s9, 31
	s_ashr_i32 s9, s9, 5
	s_add_i32 s9, s9, s10
	s_lshl_b32 s10, s9, 3
	s_sub_i32 s11, 0x80, s10
	s_min_i32 s11, s11, 8
	s_mulk_i32 s9, 0x90
	s_sub_i32 s8, s8, s9
	s_ashr_i32 s9, s8, 31
	s_abs_i32 s8, s8
	s_and_b32 s8, s8, 7
	s_add_i32 s8, s8, s10
	v_lshl_add_u32 v42, s8, 8, v91
	v_ashrrev_i32_e32 v43, 31, v42
	v_lshlrev_b64 v[42:43], 6, v[42:43]
	v_lshl_add_u64 v[46:47], v[92:93], 0, v[42:43]
	global_load_dwordx4 v[42:45], v[46:47], off offset:16
	s_nop 0
	global_load_dwordx4 v[46:49], v[46:47], off
.LBB0_752:
	s_add_u32 s4, s4, s16
	s_addc_u32 s5, s5, s17
	v_cmp_gt_i64_e32 vcc, s[4:5], v[50:51]
	s_cbranch_vccnz .LBB0_754
	s_ashr_i32 s8, s4, 31
	s_lshr_b32 s8, s8, 29
	s_add_i32 s8, s4, s8
	s_ashr_i32 s9, s8, 3
	s_and_b32 s8, s8, -8
	s_sub_i32 s8, s4, s8
	s_cmp_lt_i32 s8, 0
	s_movk_i32 s10, 0x121
	s_cselect_b32 s10, s10, 0x120
	s_mul_i32 s8, s10, s8
	s_add_i32 s8, s8, s9
	s_mul_hi_i32 s9, s8, 0x38e38e39
	s_lshr_b32 s10, s9, 31
	s_ashr_i32 s9, s9, 5
	s_add_i32 s9, s9, s10
	s_lshl_b32 s10, s9, 3
	s_sub_i32 s11, 0x80, s10
	s_min_i32 s11, s11, 8
	s_mulk_i32 s9, 0x90
	s_sub_i32 s8, s8, s9
	s_ashr_i32 s9, s8, 31
	s_abs_i32 s8, s8
	s_and_b32 s8, s8, 7
	s_add_i32 s8, s8, s10
	v_lshl_add_u32 v50, s8, 8, v91
	v_ashrrev_i32_e32 v51, 31, v50
	v_lshlrev_b64 v[50:51], 6, v[50:51]
	v_lshl_add_u64 v[54:55], v[92:93], 0, v[50:51]
	global_load_dwordx4 v[50:53], v[54:55], off offset:16
	s_nop 0
	global_load_dwordx4 v[54:57], v[54:55], off
.LBB0_754:
	s_add_u32 s4, s4, s16
	s_addc_u32 s5, s5, s17
	v_mov_b64_e32 v[66:67], 0x8ff
	v_cmp_gt_i64_e32 vcc, s[4:5], v[66:67]
	s_cbranch_vccnz .LBB0_756
	s_ashr_i32 s8, s4, 31
	s_lshr_b32 s8, s8, 29
	s_add_i32 s8, s4, s8
	s_ashr_i32 s9, s8, 3
	s_and_b32 s8, s8, -8
	s_sub_i32 s8, s4, s8
	s_cmp_lt_i32 s8, 0
	s_movk_i32 s10, 0x121
	s_cselect_b32 s10, s10, 0x120
	s_mul_i32 s8, s10, s8
	s_add_i32 s8, s8, s9
	s_mul_hi_i32 s9, s8, 0x38e38e39
	s_lshr_b32 s10, s9, 31
	s_ashr_i32 s9, s9, 5
	s_add_i32 s9, s9, s10
	s_lshl_b32 s10, s9, 3
	s_sub_i32 s11, 0x80, s10
	s_min_i32 s11, s11, 8
	s_mulk_i32 s9, 0x90
	s_sub_i32 s8, s8, s9
	s_ashr_i32 s9, s8, 31
	s_abs_i32 s8, s8
	s_and_b32 s8, s8, 7
	s_add_i32 s8, s8, s10
	v_lshl_add_u32 v58, s8, 8, v91
	v_ashrrev_i32_e32 v59, 31, v58
	v_lshlrev_b64 v[58:59], 6, v[58:59]
	v_lshl_add_u64 v[62:63], v[92:93], 0, v[58:59]
	global_load_dwordx4 v[58:61], v[62:63], off offset:16
	s_nop 0
	global_load_dwordx4 v[62:65], v[62:63], off
.LBB0_756:
	s_add_u32 s4, s4, s16
	s_addc_u32 s5, s5, s17
	v_cmp_gt_i64_e32 vcc, s[4:5], v[66:67]
	s_cbranch_vccnz .LBB0_758
	s_ashr_i32 s8, s4, 31
	s_lshr_b32 s8, s8, 29
	s_add_i32 s8, s4, s8
	s_ashr_i32 s9, s8, 3
	s_and_b32 s8, s8, -8
	s_sub_i32 s8, s4, s8
	s_cmp_lt_i32 s8, 0
	s_movk_i32 s10, 0x121
	s_cselect_b32 s10, s10, 0x120
	s_mul_i32 s8, s10, s8
	s_add_i32 s8, s8, s9
	s_mul_hi_i32 s9, s8, 0x38e38e39
	s_lshr_b32 s10, s9, 31
	s_ashr_i32 s9, s9, 5
	s_add_i32 s9, s9, s10
	s_lshl_b32 s10, s9, 3
	s_sub_i32 s11, 0x80, s10
	s_min_i32 s11, s11, 8
	s_mulk_i32 s9, 0x90
	s_sub_i32 s8, s8, s9
	s_ashr_i32 s9, s8, 31
	s_abs_i32 s8, s8
	s_and_b32 s8, s8, 7
	s_add_i32 s8, s8, s10
	v_lshl_add_u32 v66, s8, 8, v91
	v_ashrrev_i32_e32 v67, 31, v66
	v_lshlrev_b64 v[66:67], 6, v[66:67]
	v_lshl_add_u64 v[70:71], v[92:93], 0, v[66:67]
	global_load_dwordx4 v[66:69], v[70:71], off offset:16
	s_nop 0
	global_load_dwordx4 v[70:73], v[70:71], off
.LBB0_758:
	s_add_u32 s4, s4, s16
	s_addc_u32 s5, s5, s17
	v_mov_b64_e32 v[82:83], 0x8ff
	v_cmp_gt_i64_e32 vcc, s[4:5], v[82:83]
	s_cbranch_vccnz .LBB0_760
	s_ashr_i32 s8, s4, 31
	s_lshr_b32 s8, s8, 29
	s_add_i32 s8, s4, s8
	s_ashr_i32 s9, s8, 3
	s_and_b32 s8, s8, -8
	s_sub_i32 s8, s4, s8
	s_cmp_lt_i32 s8, 0
	s_movk_i32 s10, 0x121
	s_cselect_b32 s10, s10, 0x120
	s_mul_i32 s8, s10, s8
	s_add_i32 s8, s8, s9
	s_mul_hi_i32 s9, s8, 0x38e38e39
	s_lshr_b32 s10, s9, 31
	s_ashr_i32 s9, s9, 5
	s_add_i32 s9, s9, s10
	s_lshl_b32 s10, s9, 3
	s_sub_i32 s11, 0x80, s10
	s_min_i32 s11, s11, 8
	s_mulk_i32 s9, 0x90
	s_sub_i32 s8, s8, s9
	s_ashr_i32 s9, s8, 31
	s_abs_i32 s8, s8
	s_and_b32 s8, s8, 7
	s_add_i32 s8, s8, s10
	v_lshl_add_u32 v74, s8, 8, v91
	v_ashrrev_i32_e32 v75, 31, v74
	v_lshlrev_b64 v[74:75], 6, v[74:75]
	v_lshl_add_u64 v[78:79], v[92:93], 0, v[74:75]
	global_load_dwordx4 v[74:77], v[78:79], off offset:16
	s_nop 0
	global_load_dwordx4 v[78:81], v[78:79], off
.LBB0_760:
	s_add_u32 s4, s4, s16
	s_addc_u32 s5, s5, s17
	v_cmp_gt_i64_e32 vcc, s[4:5], v[82:83]
	s_cbranch_vccnz .LBB0_762
	s_ashr_i32 s8, s4, 31
	s_lshr_b32 s8, s8, 29
	s_add_i32 s8, s4, s8
	s_ashr_i32 s9, s8, 3
	s_and_b32 s8, s8, -8
	s_sub_i32 s8, s4, s8
	s_cmp_lt_i32 s8, 0
	s_movk_i32 s10, 0x121
	s_cselect_b32 s10, s10, 0x120
	s_mul_i32 s8, s10, s8
	s_add_i32 s8, s8, s9
	s_mul_hi_i32 s9, s8, 0x38e38e39
	s_lshr_b32 s10, s9, 31
	s_ashr_i32 s9, s9, 5
	s_add_i32 s9, s9, s10
	s_lshl_b32 s10, s9, 3
	s_sub_i32 s11, 0x80, s10
	s_min_i32 s11, s11, 8
	s_mulk_i32 s9, 0x90
	s_sub_i32 s8, s8, s9
	s_ashr_i32 s9, s8, 31
	s_abs_i32 s8, s8
	s_and_b32 s8, s8, 7
	s_add_i32 s8, s8, s10
	v_lshl_add_u32 v82, s8, 8, v91
	v_ashrrev_i32_e32 v83, 31, v82
	v_lshlrev_b64 v[82:83], 6, v[82:83]
	v_lshl_add_u64 v[86:87], v[92:93], 0, v[82:83]
	global_load_dwordx4 v[82:85], v[86:87], off offset:16
	s_nop 0
	global_load_dwordx4 v[86:89], v[86:87], off
.LBB0_762:
	s_add_u32 s4, s4, s16
	s_addc_u32 s5, s5, s17
	v_mov_b64_e32 v[94:95], 0x8ff
	v_cmp_gt_i64_e32 vcc, s[4:5], v[94:95]
	v_lshrrev_b32_e32 v99, 2, v0
	s_cbranch_vccnz .LBB0_764
	s_ashr_i32 s5, s4, 31
	s_lshr_b32 s5, s5, 29
	s_add_i32 s5, s4, s5
	s_ashr_i32 s8, s5, 3
	s_and_b32 s5, s5, -8
	s_sub_i32 s4, s4, s5
	s_cmp_lt_i32 s4, 0
	s_movk_i32 s5, 0x121
	s_cselect_b32 s5, s5, 0x120
	s_mul_i32 s4, s5, s4
	s_add_i32 s4, s4, s8
	s_mul_hi_i32 s5, s4, 0x38e38e39
	s_lshr_b32 s8, s5, 31
	s_ashr_i32 s5, s5, 5
	s_add_i32 s5, s5, s8
	s_lshl_b32 s8, s5, 3
	s_sub_i32 s9, 0x80, s8
	s_min_i32 s9, s9, 8
	s_mulk_i32 s5, 0x90
	s_sub_i32 s4, s4, s5
	s_ashr_i32 s5, s4, 31
	s_abs_i32 s4, s4
	s_and_b32 s4, s4, 7
	s_add_i32 s4, s4, s8
	v_lshl_add_u32 v90, s4, 8, v91
	v_ashrrev_i32_e32 v91, 31, v90
	v_lshlrev_b64 v[90:91], 6, v[90:91]
	v_lshl_add_u64 v[94:95], v[92:93], 0, v[90:91]
	global_load_dwordx4 v[90:93], v[94:95], off offset:16
	s_nop 0
	global_load_dwordx4 v[94:97], v[94:95], off

; #define S xcd_barrier(bar);
;     __device__ bool next(int i, Unit& u) const {
;         const int ti = i / nsub; u.sub = i - ti * nsub;
;         const long L = (long)ti * G + c; if (L >= nwg) return false;
;         int wgid = (int)L; { const int q = nwg / NXCD, r = nwg % NXCD, xcd = wgid % NXCD, off = wgid / NXCD; wgid = (xcd < r ? xcd * (q + 1) : r * (q + 1) + (xcd - r) * q) + off; }
;         const int nig = WGM * nN, gid = wgid / nig, fm = gid * WGM, gsz = (nM - fm) < WGM ? (nM - fm) : WGM;
;         u.pm = fm + ((wgid % nig) % gsz); u.pn = (wgid % nig) / gsz; return true;
;     }
; template <class Epi, bool ALIGN_EPI, bool ABLK = false>
; __device__ __forceinline__ void gemm_phase(PG8_LAS unsigned char* lds, const Gemm g, const StaticOrder& S, const Epi& E) {
;     ...
;         const bool has_next = S.next(ui + 1, nxt);
;         const char* nA = has_next ? PG8_ABASE(nxt) : cA; const char* nB = has_next ? PG8_BBASE(nxt) : cB;
.LBB0_815:
	s_add_i32 s45, s44, 1
	s_mul_i32 s7, s45, s16
	s_mul_hi_i32 s6, s45, s16
	s_add_u32 s10, s7, s2
	s_addc_u32 s11, s6, s19
	v_mov_b64_e32 v[130:131], 0x900
	v_cmp_gt_i64_e64 s[6:7], s[10:11], v[176:177]
	v_cmp_lt_i64_e64 s[8:9], s[10:11], v[130:131]
	s_and_b64 vcc, exec, s[6:7]
	s_cbranch_vccnz .LBB0_817
	s_ashr_i32 s11, s10, 31
	s_lshr_b32 s11, s11, 29
	s_add_i32 s11, s10, s11
	s_ashr_i32 s12, s11, 3
	s_and_b32 s11, s11, -8
	s_sub_i32 s10, s10, s11
	s_cmp_lt_i32 s10, 0
	s_movk_i32 s11, 0x121
	s_cselect_b32 s11, s11, 0x120
	s_mul_i32 s10, s11, s10
	s_add_i32 s10, s10, s12
	s_mul_hi_i32 s11, s10, 0x38e38e39
	s_lshr_b32 s12, s11, 31
	s_ashr_i32 s11, s11, 5
	s_add_i32 s11, s11, s12
	s_lshl_b32 s12, s11, 3
	s_sub_i32 s13, 0x80, s12
	s_min_i32 s13, s13, 8
	s_mulk_i32 s11, 0x90
	s_sub_i32 s10, s10, s11
	s_abs_i32 s11, s10
	s_ashr_i32 s54, s10, 3
	s_lshl_b32 s11, s54, 3
	s_and_b32 s10, s10, 7
	s_add_i32 s56, s10, s12

; #define S xcd_barrier(bar);
;     __device__ bool next(int i, Unit& u) const {
;         const int ti = i / nsub; u.sub = i - ti * nsub;
;         const long L = (long)ti * G + c; if (L >= nwg) return false;
;         int wgid = (int)L; { const int q = nwg / NXCD, r = nwg % NXCD, xcd = wgid % NXCD, off = wgid / NXCD; wgid = (xcd < r ? xcd * (q + 1) : r * (q + 1) + (xcd - r) * q) + off; }
;         const int nig = WGM * nN, gid = wgid / nig, fm = gid * WGM, gsz = (nM - fm) < WGM ? (nM - fm) : WGM;
;         u.pm = fm + ((wgid % nig) % gsz); u.pn = (wgid % nig) / gsz; return true;
;     }
; template <class Epi, bool ALIGN_EPI, bool ABLK = false>
; __device__ __forceinline__ void gemm_phase(PG8_LAS unsigned char* lds, const Gemm g, const StaticOrder& S, const Epi& E) {
;     ...
;         for (int i = 0; i < RS_MAXT; ++i) { Unit t; if (S.next(i, t)) { const float* p = E.ssqp + (size_t)(t.pm * BM + wid * 32 + (lane & 31)) * 16 + (lane >> 5) * 8; rq[i][0] = *(const f32x4*)p; rq[i][1] = *(const f32x4*)(p + 4); } }
.LBB0_1864:
	s_add_i32 s21, s23, s24
	s_ashr_i32 s23, s21, 31
	s_lshr_b32 s23, s23, 26
	s_add_i32 s23, s21, s23
	s_ashr_i32 s24, s23, 6
	s_lshl_b32 s24, s24, 3
	s_sub_i32 s25, 0x80, s24
	s_min_i32 s25, s25, 8
	s_andn2_b32 s23, s23, 63
	s_sub_i32 s21, s21, s23
	s_ashr_i32 s23, s21, 31
	s_abs_i32 s21, s21
	s_and_b32 s21, s21, 7
	s_add_i32 s24, s24, s21
	v_lshl_add_u32 v10, s24, 8, v92
	v_ashrrev_i32_e32 v11, 31, v10
	v_lshlrev_b64 v[10:11], 6, v[10:11]
	v_lshl_add_u64 v[18:19], v[90:91], 0, v[10:11]
	global_load_dwordx4 v[10:13], v[18:19], off offset:16
	global_load_dwordx4 v[14:17], v[18:19], off

; #define S xcd_barrier(bar);
;     __device__ bool next(int i, Unit& u) const {
;         const int ti = i / nsub; u.sub = i - ti * nsub;
;         const long L = (long)ti * G + c; if (L >= nwg) return false;
;         int wgid = (int)L; { const int q = nwg / NXCD, r = nwg % NXCD, xcd = wgid % NXCD, off = wgid / NXCD; wgid = (xcd < r ? xcd * (q + 1) : r * (q + 1) + (xcd - r) * q) + off; }
;         const int nig = WGM * nN, gid = wgid / nig, fm = gid * WGM, gsz = (nM - fm) < WGM ? (nM - fm) : WGM;
;         u.pm = fm + ((wgid % nig) % gsz); u.pn = (wgid % nig) / gsz; return true;
;     }
; template <class Epi, bool ALIGN_EPI, bool ABLK = false>
; __device__ __forceinline__ void gemm_phase(PG8_LAS unsigned char* lds, const Gemm g, const StaticOrder& S, const Epi& E) {
;     ...
;         for (int i = 0; i < RS_MAXT; ++i) { Unit t; if (S.next(i, t)) { const float* p = E.ssqp + (size_t)(t.pm * BM + wid * 32 + (lane & 31)) * 16 + (lane >> 5) * 8; rq[i][0] = *(const f32x4*)p; rq[i][1] = *(const f32x4*)(p + 4); } }
.LBB0_1870:
	s_add_i32 s21, s23, s24
	s_ashr_i32 s23, s21, 31
	s_lshr_b32 s23, s23, 26
	s_add_i32 s23, s21, s23
	s_ashr_i32 s24, s23, 6
	s_lshl_b32 s24, s24, 3
	s_sub_i32 s25, 0x80, s24
	s_min_i32 s25, s25, 8
	s_andn2_b32 s23, s23, 63
	s_sub_i32 s21, s21, s23
	s_ashr_i32 s23, s21, 31
	s_abs_i32 s21, s21
	s_and_b32 s21, s21, 7
	s_add_i32 s24, s24, s21
	v_lshl_add_u32 v18, s24, 8, v92
	v_ashrrev_i32_e32 v19, 31, v18
	v_lshlrev_b64 v[18:19], 6, v[18:19]
	v_lshl_add_u64 v[26:27], v[90:91], 0, v[18:19]
	global_load_dwordx4 v[18:21], v[26:27], off offset:16
	global_load_dwordx4 v[22:25], v[26:27], off

; #define S xcd_barrier(bar);
;     __device__ bool next(int i, Unit& u) const {
;         const int ti = i / nsub; u.sub = i - ti * nsub;
;         const long L = (long)ti * G + c; if (L >= nwg) return false;
;         int wgid = (int)L; { const int q = nwg / NXCD, r = nwg % NXCD, xcd = wgid % NXCD, off = wgid / NXCD; wgid = (xcd < r ? xcd * (q + 1) : r * (q + 1) + (xcd - r) * q) + off; }
;         const int nig = WGM * nN, gid = wgid / nig, fm = gid * WGM, gsz = (nM - fm) < WGM ? (nM - fm) : WGM;
;         u.pm = fm + ((wgid % nig) % gsz); u.pn = (wgid % nig) / gsz; return true;
;     }
; template <class Epi, bool ALIGN_EPI, bool ABLK = false>
; __device__ __forceinline__ void gemm_phase(PG8_LAS unsigned char* lds, const Gemm g, const StaticOrder& S, const Epi& E) {
;     ...
;         for (int i = 0; i < RS_MAXT; ++i) { Unit t; if (S.next(i, t)) { const float* p = E.ssqp + (size_t)(t.pm * BM + wid * 32 + (lane & 31)) * 16 + (lane >> 5) * 8; rq[i][0] = *(const f32x4*)p; rq[i][1] = *(const f32x4*)(p + 4); } }
.LBB0_1876:
	s_add_i32 s21, s23, s24
	s_ashr_i32 s23, s21, 31
	s_lshr_b32 s23, s23, 26
	s_add_i32 s23, s21, s23
	s_ashr_i32 s24, s23, 6
	s_lshl_b32 s24, s24, 3
	s_sub_i32 s25, 0x80, s24
	s_min_i32 s25, s25, 8
	s_andn2_b32 s23, s23, 63
	s_sub_i32 s21, s21, s23
	s_ashr_i32 s23, s21, 31
	s_abs_i32 s21, s21
	s_and_b32 s21, s21, 7
	s_add_i32 s24, s24, s21
	v_lshl_add_u32 v26, s24, 8, v92
	v_ashrrev_i32_e32 v27, 31, v26
	v_lshlrev_b64 v[26:27], 6, v[26:27]
	v_lshl_add_u64 v[34:35], v[90:91], 0, v[26:27]
	global_load_dwordx4 v[26:29], v[34:35], off offset:16
	global_load_dwordx4 v[30:33], v[34:35], off

; #define S xcd_barrier(bar);
;     __device__ bool next(int i, Unit& u) const {
;         const int ti = i / nsub; u.sub = i - ti * nsub;
;         const long L = (long)ti * G + c; if (L >= nwg) return false;
;         int wgid = (int)L; { const int q = nwg / NXCD, r = nwg % NXCD, xcd = wgid % NXCD, off = wgid / NXCD; wgid = (xcd < r ? xcd * (q + 1) : r * (q + 1) + (xcd - r) * q) + off; }
;         const int nig = WGM * nN, gid = wgid / nig, fm = gid * WGM, gsz = (nM - fm) < WGM ? (nM - fm) : WGM;
;         u.pm = fm + ((wgid % nig) % gsz); u.pn = (wgid % nig) / gsz; return true;
;     }
; template <class Epi, bool ALIGN_EPI, bool ABLK = false>
; __device__ __forceinline__ void gemm_phase(PG8_LAS unsigned char* lds, const Gemm g, const StaticOrder& S, const Epi& E) {
;     ...
;         for (int i = 0; i < RS_MAXT; ++i) { Unit t; if (S.next(i, t)) { const float* p = E.ssqp + (size_t)(t.pm * BM + wid * 32 + (lane & 31)) * 16 + (lane >> 5) * 8; rq[i][0] = *(const f32x4*)p; rq[i][1] = *(const f32x4*)(p + 4); } }
.LBB0_1882:
	s_add_i32 s21, s23, s24
	s_ashr_i32 s23, s21, 31
	s_lshr_b32 s23, s23, 26
	s_add_i32 s23, s21, s23
	s_ashr_i32 s24, s23, 6
	s_lshl_b32 s24, s24, 3
	s_sub_i32 s25, 0x80, s24
	s_min_i32 s25, s25, 8
	s_andn2_b32 s23, s23, 63
	s_sub_i32 s21, s21, s23
	s_ashr_i32 s23, s21, 31
	s_abs_i32 s21, s21
	s_and_b32 s21, s21, 7
	s_add_i32 s24, s24, s21
	v_lshl_add_u32 v34, s24, 8, v92
	v_ashrrev_i32_e32 v35, 31, v34
	v_lshlrev_b64 v[34:35], 6, v[34:35]
	v_lshl_add_u64 v[42:43], v[90:91], 0, v[34:35]
	global_load_dwordx4 v[34:37], v[42:43], off offset:16
	global_load_dwordx4 v[38:41], v[42:43], off

; #define S xcd_barrier(bar);
;     __device__ bool next(int i, Unit& u) const {
;         const int ti = i / nsub; u.sub = i - ti * nsub;
;         const long L = (long)ti * G + c; if (L >= nwg) return false;
;         int wgid = (int)L; { const int q = nwg / NXCD, r = nwg % NXCD, xcd = wgid % NXCD, off = wgid / NXCD; wgid = (xcd < r ? xcd * (q + 1) : r * (q + 1) + (xcd - r) * q) + off; }
;         const int nig = WGM * nN, gid = wgid / nig, fm = gid * WGM, gsz = (nM - fm) < WGM ? (nM - fm) : WGM;
;         u.pm = fm + ((wgid % nig) % gsz); u.pn = (wgid % nig) / gsz; return true;
;     }
; template <class Epi, bool ALIGN_EPI, bool ABLK = false>
; __device__ __forceinline__ void gemm_phase(PG8_LAS unsigned char* lds, const Gemm g, const StaticOrder& S, const Epi& E) {
;     ...
;         for (int i = 0; i < RS_MAXT; ++i) { Unit t; if (S.next(i, t)) { const float* p = E.ssqp + (size_t)(t.pm * BM + wid * 32 + (lane & 31)) * 16 + (lane >> 5) * 8; rq[i][0] = *(const f32x4*)p; rq[i][1] = *(const f32x4*)(p + 4); } }
.LBB0_1888:
	s_add_i32 s21, s23, s24
	s_ashr_i32 s23, s21, 31
	s_lshr_b32 s23, s23, 26
	s_add_i32 s23, s21, s23
	s_ashr_i32 s24, s23, 6
	s_lshl_b32 s24, s24, 3
	s_sub_i32 s25, 0x80, s24
	s_min_i32 s25, s25, 8
	s_andn2_b32 s23, s23, 63
	s_sub_i32 s21, s21, s23
	s_ashr_i32 s23, s21, 31
	s_abs_i32 s21, s21
	s_and_b32 s21, s21, 7
	s_add_i32 s24, s24, s21
	v_lshl_add_u32 v42, s24, 8, v92
	v_ashrrev_i32_e32 v43, 31, v42
	v_lshlrev_b64 v[42:43], 6, v[42:43]
	v_lshl_add_u64 v[50:51], v[90:91], 0, v[42:43]
	global_load_dwordx4 v[42:45], v[50:51], off offset:16
	global_load_dwordx4 v[46:49], v[50:51], off

; #define S xcd_barrier(bar);
;     __device__ bool next(int i, Unit& u) const {
;         const int ti = i / nsub; u.sub = i - ti * nsub;
;         const long L = (long)ti * G + c; if (L >= nwg) return false;
;         int wgid = (int)L; { const int q = nwg / NXCD, r = nwg % NXCD, xcd = wgid % NXCD, off = wgid / NXCD; wgid = (xcd < r ? xcd * (q + 1) : r * (q + 1) + (xcd - r) * q) + off; }
;         const int nig = WGM * nN, gid = wgid / nig, fm = gid * WGM, gsz = (nM - fm) < WGM ? (nM - fm) : WGM;
;         u.pm = fm + ((wgid % nig) % gsz); u.pn = (wgid % nig) / gsz; return true;
;     }
; template <class Epi, bool ALIGN_EPI, bool ABLK = false>
; __device__ __forceinline__ void gemm_phase(PG8_LAS unsigned char* lds, const Gemm g, const StaticOrder& S, const Epi& E) {
;     ...
;         for (int i = 0; i < RS_MAXT; ++i) { Unit t; if (S.next(i, t)) { const float* p = E.ssqp + (size_t)(t.pm * BM + wid * 32 + (lane & 31)) * 16 + (lane >> 5) * 8; rq[i][0] = *(const f32x4*)p; rq[i][1] = *(const f32x4*)(p + 4); } }
.LBB0_1894:
	s_add_i32 s21, s23, s24
	s_ashr_i32 s23, s21, 31
	s_lshr_b32 s23, s23, 26
	s_add_i32 s23, s21, s23
	s_ashr_i32 s24, s23, 6
	s_lshl_b32 s24, s24, 3
	s_sub_i32 s25, 0x80, s24
	s_min_i32 s25, s25, 8
	s_andn2_b32 s23, s23, 63
	s_sub_i32 s21, s21, s23
	s_ashr_i32 s23, s21, 31
	s_abs_i32 s21, s21
	s_and_b32 s21, s21, 7
	s_add_i32 s24, s24, s21
	v_lshl_add_u32 v50, s24, 8, v92
	v_ashrrev_i32_e32 v51, 31, v50
	v_lshlrev_b64 v[50:51], 6, v[50:51]
	v_lshl_add_u64 v[58:59], v[90:91], 0, v[50:51]
	global_load_dwordx4 v[50:53], v[58:59], off offset:16
	global_load_dwordx4 v[54:57], v[58:59], off

; #define S xcd_barrier(bar);
;     __device__ bool next(int i, Unit& u) const {
;         const int ti = i / nsub; u.sub = i - ti * nsub;
;         const long L = (long)ti * G + c; if (L >= nwg) return false;
;         int wgid = (int)L; { const int q = nwg / NXCD, r = nwg % NXCD, xcd = wgid % NXCD, off = wgid / NXCD; wgid = (xcd < r ? xcd * (q + 1) : r * (q + 1) + (xcd - r) * q) + off; }
;         const int nig = WGM * nN, gid = wgid / nig, fm = gid * WGM, gsz = (nM - fm) < WGM ? (nM - fm) : WGM;
;         u.pm = fm + ((wgid % nig) % gsz); u.pn = (wgid % nig) / gsz; return true;
;     }
; template <class Epi, bool ALIGN_EPI, bool ABLK = false>
; __device__ __forceinline__ void gemm_phase(PG8_LAS unsigned char* lds, const Gemm g, const StaticOrder& S, const Epi& E) {
;     ...
;         for (int i = 0; i < RS_MAXT; ++i) { Unit t; if (S.next(i, t)) { const float* p = E.ssqp + (size_t)(t.pm * BM + wid * 32 + (lane & 31)) * 16 + (lane >> 5) * 8; rq[i][0] = *(const f32x4*)p; rq[i][1] = *(const f32x4*)(p + 4); } }
.LBB0_1900:
	s_add_i32 s21, s23, s24
	s_ashr_i32 s23, s21, 31
	s_lshr_b32 s23, s23, 26
	s_add_i32 s23, s21, s23
	s_ashr_i32 s24, s23, 6
	s_lshl_b32 s24, s24, 3
	s_sub_i32 s25, 0x80, s24
	s_min_i32 s25, s25, 8
	s_andn2_b32 s23, s23, 63
	s_sub_i32 s21, s21, s23
	s_ashr_i32 s23, s21, 31
	s_abs_i32 s21, s21
	s_and_b32 s21, s21, 7
	s_add_i32 s24, s24, s21
	v_lshl_add_u32 v58, s24, 8, v92
	v_ashrrev_i32_e32 v59, 31, v58
	v_lshlrev_b64 v[58:59], 6, v[58:59]
	v_lshl_add_u64 v[66:67], v[90:91], 0, v[58:59]
	global_load_dwordx4 v[58:61], v[66:67], off offset:16
	global_load_dwordx4 v[62:65], v[66:67], off

; #define S xcd_barrier(bar);
;     __device__ bool next(int i, Unit& u) const {
;         const int ti = i / nsub; u.sub = i - ti * nsub;
;         const long L = (long)ti * G + c; if (L >= nwg) return false;
;         int wgid = (int)L; { const int q = nwg / NXCD, r = nwg % NXCD, xcd = wgid % NXCD, off = wgid / NXCD; wgid = (xcd < r ? xcd * (q + 1) : r * (q + 1) + (xcd - r) * q) + off; }
;         const int nig = WGM * nN, gid = wgid / nig, fm = gid * WGM, gsz = (nM - fm) < WGM ? (nM - fm) : WGM;
;         u.pm = fm + ((wgid % nig) % gsz); u.pn = (wgid % nig) / gsz; return true;
;     }
; template <class Epi, bool ALIGN_EPI, bool ABLK = false>
; __device__ __forceinline__ void gemm_phase(PG8_LAS unsigned char* lds, const Gemm g, const StaticOrder& S, const Epi& E) {
;     ...
;         for (int i = 0; i < RS_MAXT; ++i) { Unit t; if (S.next(i, t)) { const float* p = E.ssqp + (size_t)(t.pm * BM + wid * 32 + (lane & 31)) * 16 + (lane >> 5) * 8; rq[i][0] = *(const f32x4*)p; rq[i][1] = *(const f32x4*)(p + 4); } }
.LBB0_1906:
	s_add_i32 s21, s23, s24
	s_ashr_i32 s23, s21, 31
	s_lshr_b32 s23, s23, 26
	s_add_i32 s23, s21, s23
	s_ashr_i32 s24, s23, 6
	s_lshl_b32 s24, s24, 3
	s_sub_i32 s25, 0x80, s24
	s_min_i32 s25, s25, 8
	s_andn2_b32 s23, s23, 63
	s_sub_i32 s21, s21, s23
	s_ashr_i32 s23, s21, 31
	s_abs_i32 s21, s21
	s_and_b32 s21, s21, 7
	s_add_i32 s24, s24, s21
	v_lshl_add_u32 v66, s24, 8, v92
	v_ashrrev_i32_e32 v67, 31, v66
	v_lshlrev_b64 v[66:67], 6, v[66:67]
	v_lshl_add_u64 v[74:75], v[90:91], 0, v[66:67]
	global_load_dwordx4 v[66:69], v[74:75], off offset:16
	global_load_dwordx4 v[70:73], v[74:75], off

; #define S xcd_barrier(bar);
;     __device__ bool next(int i, Unit& u) const {
;         const int ti = i / nsub; u.sub = i - ti * nsub;
;         const long L = (long)ti * G + c; if (L >= nwg) return false;
;         int wgid = (int)L; { const int q = nwg / NXCD, r = nwg % NXCD, xcd = wgid % NXCD, off = wgid / NXCD; wgid = (xcd < r ? xcd * (q + 1) : r * (q + 1) + (xcd - r) * q) + off; }
;         const int nig = WGM * nN, gid = wgid / nig, fm = gid * WGM, gsz = (nM - fm) < WGM ? (nM - fm) : WGM;
;         u.pm = fm + ((wgid % nig) % gsz); u.pn = (wgid % nig) / gsz; return true;
;     }
; template <class Epi, bool ALIGN_EPI, bool ABLK = false>
; __device__ __forceinline__ void gemm_phase(PG8_LAS unsigned char* lds, const Gemm g, const StaticOrder& S, const Epi& E) {
;     ...
;         for (int i = 0; i < RS_MAXT; ++i) { Unit t; if (S.next(i, t)) { const float* p = E.ssqp + (size_t)(t.pm * BM + wid * 32 + (lane & 31)) * 16 + (lane >> 5) * 8; rq[i][0] = *(const f32x4*)p; rq[i][1] = *(const f32x4*)(p + 4); } }
.LBB0_1912:
	s_add_i32 s21, s23, s24
	s_ashr_i32 s23, s21, 31
	s_lshr_b32 s23, s23, 26
	s_add_i32 s23, s21, s23
	s_ashr_i32 s24, s23, 6
	s_lshl_b32 s24, s24, 3
	s_sub_i32 s25, 0x80, s24
	s_min_i32 s25, s25, 8
	s_andn2_b32 s23, s23, 63
	s_sub_i32 s21, s21, s23
	s_ashr_i32 s23, s21, 31
	s_abs_i32 s21, s21
	s_and_b32 s21, s21, 7
	s_add_i32 s24, s24, s21
	v_lshl_add_u32 v74, s24, 8, v92
	v_ashrrev_i32_e32 v75, 31, v74
	v_lshlrev_b64 v[74:75], 6, v[74:75]
	v_lshl_add_u64 v[82:83], v[90:91], 0, v[74:75]
	global_load_dwordx4 v[74:77], v[82:83], off offset:16
	global_load_dwordx4 v[78:81], v[82:83], off

; #define S xcd_barrier(bar);
;     __device__ bool next(int i, Unit& u) const {
;         const int ti = i / nsub; u.sub = i - ti * nsub;
;         const long L = (long)ti * G + c; if (L >= nwg) return false;
;         int wgid = (int)L; { const int q = nwg / NXCD, r = nwg % NXCD, xcd = wgid % NXCD, off = wgid / NXCD; wgid = (xcd < r ? xcd * (q + 1) : r * (q + 1) + (xcd - r) * q) + off; }
;         const int nig = WGM * nN, gid = wgid / nig, fm = gid * WGM, gsz = (nM - fm) < WGM ? (nM - fm) : WGM;
;         u.pm = fm + ((wgid % nig) % gsz); u.pn = (wgid % nig) / gsz; return true;
;     }
; template <class Epi, bool ALIGN_EPI, bool ABLK = false>
; __device__ __forceinline__ void gemm_phase(PG8_LAS unsigned char* lds, const Gemm g, const StaticOrder& S, const Epi& E) {
;     ...
;         for (int i = 0; i < RS_MAXT; ++i) { Unit t; if (S.next(i, t)) { const float* p = E.ssqp + (size_t)(t.pm * BM + wid * 32 + (lane & 31)) * 16 + (lane >> 5) * 8; rq[i][0] = *(const f32x4*)p; rq[i][1] = *(const f32x4*)(p + 4); } }
.LBB0_1918:
	s_add_i32 s21, s23, s24
	s_ashr_i32 s23, s21, 31
	s_lshr_b32 s23, s23, 26
	s_add_i32 s23, s21, s23
	s_ashr_i32 s24, s23, 6
	s_lshl_b32 s24, s24, 3
	s_sub_i32 s25, 0x80, s24
	s_min_i32 s25, s25, 8
	s_andn2_b32 s23, s23, 63
	s_sub_i32 s21, s21, s23
	s_ashr_i32 s23, s21, 31
	s_abs_i32 s21, s21
	s_and_b32 s21, s21, 7
	s_add_i32 s24, s24, s21
	v_lshl_add_u32 v82, s24, 8, v92
	v_ashrrev_i32_e32 v83, 31, v82
	v_lshlrev_b64 v[82:83], 6, v[82:83]
	v_lshl_add_u64 v[94:95], v[90:91], 0, v[82:83]
	global_load_dwordx4 v[82:85], v[94:95], off offset:16
	global_load_dwordx4 v[86:89], v[94:95], off

; #define S xcd_barrier(bar);
;     __device__ bool next(int i, Unit& u) const {
;         const int ti = i / nsub; u.sub = i - ti * nsub;
;         const long L = (long)ti * G + c; if (L >= nwg) return false;
;         int wgid = (int)L; { const int q = nwg / NXCD, r = nwg % NXCD, xcd = wgid % NXCD, off = wgid / NXCD; wgid = (xcd < r ? xcd * (q + 1) : r * (q + 1) + (xcd - r) * q) + off; }
;         const int nig = WGM * nN, gid = wgid / nig, fm = gid * WGM, gsz = (nM - fm) < WGM ? (nM - fm) : WGM;
;         u.pm = fm + ((wgid % nig) % gsz); u.pn = (wgid % nig) / gsz; return true;
;     }
; template <class Epi, bool ALIGN_EPI, bool ABLK = false>
; __device__ __forceinline__ void gemm_phase(PG8_LAS unsigned char* lds, const Gemm g, const StaticOrder& S, const Epi& E) {
;     ...
;         for (int i = 0; i < RS_MAXT; ++i) { Unit t; if (S.next(i, t)) { const float* p = E.ssqp + (size_t)(t.pm * BM + wid * 32 + (lane & 31)) * 16 + (lane >> 5) * 8; rq[i][0] = *(const f32x4*)p; rq[i][1] = *(const f32x4*)(p + 4); } }
.LBB0_1924:
	s_add_i32 s4, s23, s4
	s_ashr_i32 s5, s4, 31
	s_lshr_b32 s5, s5, 26
	s_add_i32 s5, s4, s5
	s_ashr_i32 s21, s5, 6
	s_lshl_b32 s21, s21, 3
	s_sub_i32 s23, 0x80, s21
	s_min_i32 s23, s23, 8
	s_andn2_b32 s5, s5, 63
	s_sub_i32 s4, s4, s5
	s_ashr_i32 s5, s4, 31
	s_abs_i32 s4, s4
	s_and_b32 s4, s4, 7
	s_add_i32 s21, s21, s4
	v_lshl_add_u32 v92, s21, 8, v92
	v_ashrrev_i32_e32 v93, 31, v92
	v_lshlrev_b64 v[92:93], 6, v[92:93]
	v_lshl_add_u64 v[100:101], v[90:91], 0, v[92:93]
	global_load_dwordx4 v[90:93], v[100:101], off offset:16
	global_load_dwordx4 v[94:97], v[100:101], off

; #define S xcd_barrier(bar);
;     __device__ bool next(int i, Unit& u) const {
;         const int ti = i / nsub; u.sub = i - ti * nsub;
;         const long L = (long)ti * G + c; if (L >= nwg) return false;
;         int wgid = (int)L; { const int q = nwg / NXCD, r = nwg % NXCD, xcd = wgid % NXCD, off = wgid / NXCD; wgid = (xcd < r ? xcd * (q + 1) : r * (q + 1) + (xcd - r) * q) + off; }
;         const int nig = WGM * nN, gid = wgid / nig, fm = gid * WGM, gsz = (nM - fm) < WGM ? (nM - fm) : WGM;
;         u.pm = fm + ((wgid % nig) % gsz); u.pn = (wgid % nig) / gsz; return true;
;     }
; template <class Epi, bool ALIGN_EPI, bool ABLK = false>
; __device__ __forceinline__ void gemm_phase(PG8_LAS unsigned char* lds, const Gemm g, const StaticOrder& S, const Epi& E) {
;     ...
;         const bool has_next = S.next(ui + 1, nxt);
;         const char* nA = has_next ? PG8_ABASE(nxt) : cA; const char* nB = has_next ? PG8_BBASE(nxt) : cB;
.LBB0_1981:
	s_ashr_i32 s52, s54, 3
	s_add_i32 s52, s56, s52
	s_ashr_i32 s53, s52, 31
	s_lshr_b32 s53, s53, 26
	s_add_i32 s53, s52, s53
	s_ashr_i32 s54, s53, 6
	s_lshl_b32 s54, s54, 3
	s_sub_i32 s55, 0x80, s54
	s_min_i32 s55, s55, 8
	s_andn2_b32 s53, s53, 63
	s_sub_i32 s53, s52, s53
	s_abs_i32 s52, s53
	s_ashr_i32 s52, s53, 3
	s_lshl_b32 s55, s52, 3
	s_and_b32 s53, s53, 7
	s_add_i32 s54, s54, s53

; #define S xcd_barrier(bar);
;     __device__ bool next(int i, Unit& u) const {
;         const int ti = i / nsub; u.sub = i - ti * nsub;
;         const long L = (long)ti * G + c; if (L >= nwg) return false;
;         int wgid = (int)L; { const int q = nwg / NXCD, r = nwg % NXCD, xcd = wgid % NXCD, off = wgid / NXCD; wgid = (xcd < r ? xcd * (q + 1) : r * (q + 1) + (xcd - r) * q) + off; }
;         const int nig = WGM * nN, gid = wgid / nig, fm = gid * WGM, gsz = (nM - fm) < WGM ? (nM - fm) : WGM;
;         u.pm = fm + ((wgid % nig) % gsz); u.pn = (wgid % nig) / gsz; return true;
;     }
; template <class Epi, bool ALIGN_EPI, bool ABLK = false>
; __device__ __forceinline__ void gemm_phase(PG8_LAS unsigned char* lds, const Gemm g, const StaticOrder& S, const Epi& E) {
;     ...
;         const bool has_next = S.next(ui + 1, nxt);
;         const char* nA = has_next ? PG8_ABASE(nxt) : cA; const char* nB = has_next ? PG8_BBASE(nxt) : cB;
.LBB0_2103:
	s_ashr_i32 s40, s42, 3
	s_add_i32 s40, s44, s40
	s_ashr_i32 s41, s40, 31
	s_lshr_b32 s41, s41, 27
	s_add_i32 s41, s40, s41
	s_ashr_i32 s42, s41, 5
	s_lshl_b32 s42, s42, 3
	s_sub_i32 s43, 0x80, s42
	s_min_i32 s43, s43, 8
	s_andn2_b32 s41, s41, 31
	s_sub_i32 s41, s40, s41
	s_abs_i32 s40, s41
	s_ashr_i32 s40, s41, 3
	s_lshl_b32 s43, s40, 3
	s_and_b32 s41, s41, 7
	s_add_i32 s42, s42, s41

; #define S xcd_barrier(bar);
;     __device__ bool next(int i, Unit& u) const {
;         const int ti = i / nsub; u.sub = i - ti * nsub;
;         const long L = (long)ti * G + c; if (L >= nwg) return false;
;         int wgid = (int)L; { const int q = nwg / NXCD, r = nwg % NXCD, xcd = wgid % NXCD, off = wgid / NXCD; wgid = (xcd < r ? xcd * (q + 1) : r * (q + 1) + (xcd - r) * q) + off; }
;         const int nig = WGM * nN, gid = wgid / nig, fm = gid * WGM, gsz = (nM - fm) < WGM ? (nM - fm) : WGM;
;         u.pm = fm + ((wgid % nig) % gsz); u.pn = (wgid % nig) / gsz; return true;
;     }
; template <class Epi, bool ALIGN_EPI, bool ABLK = false>
; __device__ __forceinline__ void gemm_phase(PG8_LAS unsigned char* lds, const Gemm g, const StaticOrder& S, const Epi& E) {
;     ...
;         const bool has_next = S.next(ui + 1, nxt);
;         const char* nA = has_next ? PG8_ABASE(nxt) : cA; const char* nB = has_next ? PG8_BBASE(nxt) : cB;
.LBB0_2287:
	s_ashr_i32 s48, s50, 3
	s_add_i32 s48, s52, s48
	s_ashr_i32 s49, s48, 31
	s_lshr_b32 s49, s49, 27
	s_add_i32 s49, s48, s49
	s_ashr_i32 s50, s49, 5
	s_lshl_b32 s50, s50, 3
	s_sub_i32 s51, 0x80, s50
	s_min_i32 s51, s51, 8
	s_andn2_b32 s49, s49, 31
	s_sub_i32 s49, s48, s49
	s_abs_i32 s48, s49
	s_ashr_i32 s48, s49, 3
	s_lshl_b32 s51, s48, 3
	s_and_b32 s49, s49, 7
	s_add_i32 s50, s50, s49

; #define S xcd_barrier(bar);
;     __device__ bool next(int i, Unit& u) const {
;         const int ti = i / nsub; u.sub = i - ti * nsub;
;         const long L = (long)ti * G + c; if (L >= nwg) return false;
;         int wgid = (int)L; { const int q = nwg / NXCD, r = nwg % NXCD, xcd = wgid % NXCD, off = wgid / NXCD; wgid = (xcd < r ? xcd * (q + 1) : r * (q + 1) + (xcd - r) * q) + off; }
;         const int nig = WGM * nN, gid = wgid / nig, fm = gid * WGM, gsz = (nM - fm) < WGM ? (nM - fm) : WGM;
;         u.pm = fm + ((wgid % nig) % gsz); u.pn = (wgid % nig) / gsz; return true;
;     }
; template <class Epi, bool ALIGN_EPI, bool ABLK = false>
; __device__ __forceinline__ void gemm_phase(PG8_LAS unsigned char* lds, const Gemm g, const StaticOrder& S, const Epi& E) {
;     ...
;         for (int i = 0; i < RS_MAXT; ++i) { Unit t; if (S.next(i, t)) { const float* p = E.ssqp + (size_t)(t.pm * BM + wid * 32 + (lane & 31)) * 16 + (lane >> 5) * 8; rq[i][0] = *(const f32x4*)p; rq[i][1] = *(const f32x4*)(p + 4); } }
.LBB0_2418:
	s_andn2_b64 vcc, exec, s[4:5]
	s_cbranch_vccnz .LBB0_2506
	s_add_u32 s6, s96, 0x3908000
	s_addc_u32 s7, s97, 0
	s_ashr_i32 s65, s2, 31
	s_lshr_b32 s4, s65, 29
	s_add_i32 s4, s2, s4
	s_lshr_b32 s30, s38, 6
	s_ashr_i32 s5, s4, 3
	s_and_b32 s4, s4, -8
	s_ashr_i32 s17, s16, 31
	s_lshl_b32 s26, s30, 5
	s_sub_i32 s4, s2, s4
	s_cmp_lt_i32 s4, 0
	s_movk_i32 s9, 0x161
	s_cselect_b32 s11, s9, 0x160
	s_mul_i32 s4, s11, s4
	s_add_i32 s4, s4, s5
	s_mul_hi_i32 s5, s4, 0x2e8ba2e9
	s_lshr_b32 s11, s5, 31
	s_ashr_i32 s5, s5, 5
	s_add_i32 s5, s5, s11
	s_mul_i32 s11, s5, 0xb0
	s_sub_i32 s4, s4, s11
	s_bfe_u32 s11, s4, 0x3001c
	s_add_i32 s11, s4, s11
	s_and_b32 s11, s11, 0xfff8
	s_sub_i32 s4, s4, s11
	s_sext_i32_i16 s4, s4
	s_lshl_b32 s5, s5, 11
	s_lshl_b32 s4, s4, 8
	v_and_or_b32 v91, v0, 31, s26
	s_add_i32 s4, s4, s5
	v_add_u32_e32 v2, s4, v91
	v_and_b32_e32 v98, 32, v0
	v_mov_b32_e32 v99, 0
	v_ashrrev_i32_e32 v3, 31, v2
	v_lshl_add_u64 v[92:93], s[6:7], 0, v[98:99]
	v_lshlrev_b64 v[2:3], 6, v[2:3]
	v_lshl_add_u64 v[10:11], v[92:93], 0, v[2:3]
	global_load_dwordx4 v[2:5], v[10:11], off offset:16
	global_load_dwordx4 v[6:9], v[10:11], off
	s_add_u32 s4, s16, s2
	s_addc_u32 s5, s17, s65
	v_mov_b64_e32 v[18:19], 0xaff
	v_cmp_gt_i64_e32 vcc, s[4:5], v[18:19]
	s_cbranch_vccnz .LBB0_2421
	s_ashr_i32 s11, s4, 31
	s_lshr_b32 s11, s11, 29
	s_add_i32 s11, s4, s11
	s_ashr_i32 s22, s11, 3
	s_and_b32 s11, s11, -8
	s_sub_i32 s11, s4, s11
	s_cmp_lt_i32 s11, 0
	s_cselect_b32 s9, s9, 0x160
	s_mul_i32 s9, s9, s11
	s_add_i32 s9, s9, s22
	s_mul_hi_i32 s11, s9, 0x2e8ba2e9
	s_lshr_b32 s22, s11, 31
	s_ashr_i32 s11, s11, 5
	s_add_i32 s11, s11, s22
	s_lshl_b32 s22, s11, 3
	s_sub_i32 s23, 0x80, s22
	s_min_i32 s23, s23, 8
	s_mulk_i32 s11, 0xb0
	s_sub_i32 s9, s9, s11
	s_ashr_i32 s11, s9, 31
	s_abs_i32 s9, s9
	s_and_b32 s9, s9, 7
	s_add_i32 s9, s9, s22
	v_lshl_add_u32 v10, s9, 8, v91
	v_ashrrev_i32_e32 v11, 31, v10
	v_lshlrev_b64 v[10:11], 6, v[10:11]
	v_lshl_add_u64 v[20:21], v[92:93], 0, v[10:11]
	global_load_dwordx4 v[10:13], v[20:21], off offset:16
	global_load_dwordx4 v[14:17], v[20:21], off
.LBB0_2421:
	s_add_u32 s4, s4, s16
	s_addc_u32 s5, s5, s17
	v_cmp_gt_i64_e32 vcc, s[4:5], v[18:19]
	s_cbranch_vccnz .LBB0_2423
	s_ashr_i32 s9, s4, 31
	s_lshr_b32 s9, s9, 29
	s_add_i32 s9, s4, s9
	s_ashr_i32 s11, s9, 3
	s_and_b32 s9, s9, -8
	s_sub_i32 s9, s4, s9
	s_cmp_lt_i32 s9, 0
	s_movk_i32 s22, 0x161
	s_cselect_b32 s22, s22, 0x160
	s_mul_i32 s9, s22, s9
	s_add_i32 s9, s9, s11
	s_mul_hi_i32 s11, s9, 0x2e8ba2e9
	s_lshr_b32 s22, s11, 31
	s_ashr_i32 s11, s11, 5
	s_add_i32 s11, s11, s22
	s_lshl_b32 s22, s11, 3
	s_sub_i32 s23, 0x80, s22
	s_min_i32 s23, s23, 8
	s_mulk_i32 s11, 0xb0
	s_sub_i32 s9, s9, s11
	s_ashr_i32 s11, s9, 31
	s_abs_i32 s9, s9
	s_and_b32 s9, s9, 7
	s_add_i32 s9, s9, s22
	v_lshl_add_u32 v18, s9, 8, v91
	v_ashrrev_i32_e32 v19, 31, v18
	v_lshlrev_b64 v[18:19], 6, v[18:19]
	v_lshl_add_u64 v[26:27], v[92:93], 0, v[18:19]
	global_load_dwordx4 v[18:21], v[26:27], off offset:16
	global_load_dwordx4 v[22:25], v[26:27], off
.LBB0_2423:
	s_add_u32 s4, s4, s16
	s_addc_u32 s5, s5, s17
	v_mov_b64_e32 v[34:35], 0xaff
	v_cmp_gt_i64_e32 vcc, s[4:5], v[34:35]
	s_cbranch_vccnz .LBB0_2425
	s_ashr_i32 s9, s4, 31
	s_lshr_b32 s9, s9, 29
	s_add_i32 s9, s4, s9
	s_ashr_i32 s11, s9, 3
	s_and_b32 s9, s9, -8
	s_sub_i32 s9, s4, s9
	s_cmp_lt_i32 s9, 0
	s_movk_i32 s22, 0x161
	s_cselect_b32 s22, s22, 0x160
	s_mul_i32 s9, s22, s9
	s_add_i32 s9, s9, s11
	s_mul_hi_i32 s11, s9, 0x2e8ba2e9
	s_lshr_b32 s22, s11, 31
	s_ashr_i32 s11, s11, 5
	s_add_i32 s11, s11, s22
	s_lshl_b32 s22, s11, 3
	s_sub_i32 s23, 0x80, s22
	s_min_i32 s23, s23, 8
	s_mulk_i32 s11, 0xb0
	s_sub_i32 s9, s9, s11
	s_ashr_i32 s11, s9, 31
	s_abs_i32 s9, s9
	s_and_b32 s9, s9, 7
	s_add_i32 s9, s9, s22
	v_lshl_add_u32 v26, s9, 8, v91
	v_ashrrev_i32_e32 v27, 31, v26
	v_lshlrev_b64 v[26:27], 6, v[26:27]
	v_lshl_add_u64 v[36:37], v[92:93], 0, v[26:27]
	global_load_dwordx4 v[26:29], v[36:37], off offset:16
	global_load_dwordx4 v[30:33], v[36:37], off
.LBB0_2425:
	s_add_u32 s4, s4, s16
	s_addc_u32 s5, s5, s17
	v_cmp_gt_i64_e32 vcc, s[4:5], v[34:35]
	s_cbranch_vccnz .LBB0_2427
	s_ashr_i32 s9, s4, 31
	s_lshr_b32 s9, s9, 29
	s_add_i32 s9, s4, s9
	s_ashr_i32 s11, s9, 3
	s_and_b32 s9, s9, -8
	s_sub_i32 s9, s4, s9
	s_cmp_lt_i32 s9, 0
	s_movk_i32 s22, 0x161
	s_cselect_b32 s22, s22, 0x160
	s_mul_i32 s9, s22, s9
	s_add_i32 s9, s9, s11
	s_mul_hi_i32 s11, s9, 0x2e8ba2e9
	s_lshr_b32 s22, s11, 31
	s_ashr_i32 s11, s11, 5
	s_add_i32 s11, s11, s22
	s_lshl_b32 s22, s11, 3
	s_sub_i32 s23, 0x80, s22
	s_min_i32 s23, s23, 8
	s_mulk_i32 s11, 0xb0
	s_sub_i32 s9, s9, s11
	s_ashr_i32 s11, s9, 31
	s_abs_i32 s9, s9
	s_and_b32 s9, s9, 7
	s_add_i32 s9, s9, s22
	v_lshl_add_u32 v34, s9, 8, v91
	v_ashrrev_i32_e32 v35, 31, v34
	v_lshlrev_b64 v[34:35], 6, v[34:35]
	v_lshl_add_u64 v[42:43], v[92:93], 0, v[34:35]
	global_load_dwordx4 v[34:37], v[42:43], off offset:16
	global_load_dwordx4 v[38:41], v[42:43], off
.LBB0_2427:
	s_add_u32 s4, s4, s16
	s_addc_u32 s5, s5, s17
	v_mov_b64_e32 v[50:51], 0xaff
	v_cmp_gt_i64_e32 vcc, s[4:5], v[50:51]
	s_cbranch_vccnz .LBB0_2429
	s_ashr_i32 s9, s4, 31
	s_lshr_b32 s9, s9, 29
	s_add_i32 s9, s4, s9
	s_ashr_i32 s11, s9, 3
	s_and_b32 s9, s9, -8
	s_sub_i32 s9, s4, s9
	s_cmp_lt_i32 s9, 0
	s_movk_i32 s22, 0x161
	s_cselect_b32 s22, s22, 0x160
	s_mul_i32 s9, s22, s9
	s_add_i32 s9, s9, s11
	s_mul_hi_i32 s11, s9, 0x2e8ba2e9
	s_lshr_b32 s22, s11, 31
	s_ashr_i32 s11, s11, 5
	s_add_i32 s11, s11, s22
	s_lshl_b32 s22, s11, 3
	s_sub_i32 s23, 0x80, s22
	s_min_i32 s23, s23, 8
	s_mulk_i32 s11, 0xb0
	s_sub_i32 s9, s9, s11
	s_ashr_i32 s11, s9, 31
	s_abs_i32 s9, s9
	s_and_b32 s9, s9, 7
	s_add_i32 s9, s9, s22
	v_lshl_add_u32 v42, s9, 8, v91
	v_ashrrev_i32_e32 v43, 31, v42
	v_lshlrev_b64 v[42:43], 6, v[42:43]
	v_lshl_add_u64 v[52:53], v[92:93], 0, v[42:43]
	global_load_dwordx4 v[42:45], v[52:53], off offset:16
	global_load_dwordx4 v[46:49], v[52:53], off
; #define S xcd_barrier(bar);
;     __device__ bool next(int i, Unit& u) const {
;         const int ti = i / nsub; u.sub = i - ti * nsub;
;         const long L = (long)ti * G + c; if (L >= nwg) return false;
;         int wgid = (int)L; { const int q = nwg / NXCD, r = nwg % NXCD, xcd = wgid % NXCD, off = wgid / NXCD; wgid = (xcd < r ? xcd * (q + 1) : r * (q + 1) + (xcd - r) * q) + off; }
;         const int nig = WGM * nN, gid = wgid / nig, fm = gid * WGM, gsz = (nM - fm) < WGM ? (nM - fm) : WGM;
;         u.pm = fm + ((wgid % nig) % gsz); u.pn = (wgid % nig) / gsz; return true;
;     }
; template <class Epi, bool ALIGN_EPI, bool ABLK = false>
; __device__ __forceinline__ void gemm_phase(PG8_LAS unsigned char* lds, const Gemm g, const StaticOrder& S, const Epi& E) {
;     ...
;         for (int i = 0; i < RS_MAXT; ++i) { Unit t; if (S.next(i, t)) { const float* p = E.ssqp + (size_t)(t.pm * BM + wid * 32 + (lane & 31)) * 16 + (lane >> 5) * 8; rq[i][0] = *(const f32x4*)p; rq[i][1] = *(const f32x4*)(p + 4); } }
.LBB0_2429:
	s_add_u32 s4, s4, s16
	s_addc_u32 s5, s5, s17
	v_cmp_gt_i64_e32 vcc, s[4:5], v[50:51]
	s_cbranch_vccnz .LBB0_2431
	s_ashr_i32 s9, s4, 31
	s_lshr_b32 s9, s9, 29
	s_add_i32 s9, s4, s9
	s_ashr_i32 s11, s9, 3
	s_and_b32 s9, s9, -8
	s_sub_i32 s9, s4, s9
	s_cmp_lt_i32 s9, 0
	s_movk_i32 s22, 0x161
	s_cselect_b32 s22, s22, 0x160
	s_mul_i32 s9, s22, s9
	s_add_i32 s9, s9, s11
	s_mul_hi_i32 s11, s9, 0x2e8ba2e9
	s_lshr_b32 s22, s11, 31
	s_ashr_i32 s11, s11, 5
	s_add_i32 s11, s11, s22
	s_lshl_b32 s22, s11, 3
	s_sub_i32 s23, 0x80, s22
	s_min_i32 s23, s23, 8
	s_mulk_i32 s11, 0xb0
	s_sub_i32 s9, s9, s11
	s_ashr_i32 s11, s9, 31
	s_abs_i32 s9, s9
	s_and_b32 s9, s9, 7
	s_add_i32 s9, s9, s22
	v_lshl_add_u32 v50, s9, 8, v91
	v_ashrrev_i32_e32 v51, 31, v50
	v_lshlrev_b64 v[50:51], 6, v[50:51]
	v_lshl_add_u64 v[58:59], v[92:93], 0, v[50:51]
	global_load_dwordx4 v[50:53], v[58:59], off offset:16
	global_load_dwordx4 v[54:57], v[58:59], off
.LBB0_2431:
	s_add_u32 s4, s4, s16
	s_addc_u32 s5, s5, s17
	v_mov_b64_e32 v[66:67], 0xaff
	v_cmp_gt_i64_e32 vcc, s[4:5], v[66:67]
	s_cbranch_vccnz .LBB0_2433
	s_ashr_i32 s9, s4, 31
	s_lshr_b32 s9, s9, 29
	s_add_i32 s9, s4, s9
	s_ashr_i32 s11, s9, 3
	s_and_b32 s9, s9, -8
	s_sub_i32 s9, s4, s9
	s_cmp_lt_i32 s9, 0
	s_movk_i32 s22, 0x161
	s_cselect_b32 s22, s22, 0x160
	s_mul_i32 s9, s22, s9
	s_add_i32 s9, s9, s11
	s_mul_hi_i32 s11, s9, 0x2e8ba2e9
	s_lshr_b32 s22, s11, 31
	s_ashr_i32 s11, s11, 5
	s_add_i32 s11, s11, s22
	s_lshl_b32 s22, s11, 3
	s_sub_i32 s23, 0x80, s22
	s_min_i32 s23, s23, 8
	s_mulk_i32 s11, 0xb0
	s_sub_i32 s9, s9, s11
	s_ashr_i32 s11, s9, 31
	s_abs_i32 s9, s9
	s_and_b32 s9, s9, 7
	s_add_i32 s9, s9, s22
	v_lshl_add_u32 v58, s9, 8, v91
	v_ashrrev_i32_e32 v59, 31, v58
	v_lshlrev_b64 v[58:59], 6, v[58:59]
	v_lshl_add_u64 v[68:69], v[92:93], 0, v[58:59]
	global_load_dwordx4 v[58:61], v[68:69], off offset:16
	global_load_dwordx4 v[62:65], v[68:69], off
.LBB0_2433:
	s_add_u32 s4, s4, s16
	s_addc_u32 s5, s5, s17
	v_cmp_gt_i64_e32 vcc, s[4:5], v[66:67]
	s_cbranch_vccnz .LBB0_2435
	s_ashr_i32 s9, s4, 31
	s_lshr_b32 s9, s9, 29
	s_add_i32 s9, s4, s9
	s_ashr_i32 s11, s9, 3
	s_and_b32 s9, s9, -8
	s_sub_i32 s9, s4, s9
	s_cmp_lt_i32 s9, 0
	s_movk_i32 s22, 0x161
	s_cselect_b32 s22, s22, 0x160
	s_mul_i32 s9, s22, s9
	s_add_i32 s9, s9, s11
	s_mul_hi_i32 s11, s9, 0x2e8ba2e9
	s_lshr_b32 s22, s11, 31
	s_ashr_i32 s11, s11, 5
	s_add_i32 s11, s11, s22
	s_lshl_b32 s22, s11, 3
	s_sub_i32 s23, 0x80, s22
	s_min_i32 s23, s23, 8
	s_mulk_i32 s11, 0xb0
	s_sub_i32 s9, s9, s11
	s_ashr_i32 s11, s9, 31
	s_abs_i32 s9, s9
	s_and_b32 s9, s9, 7
	s_add_i32 s9, s9, s22
	v_lshl_add_u32 v66, s9, 8, v91
	v_ashrrev_i32_e32 v67, 31, v66
	v_lshlrev_b64 v[66:67], 6, v[66:67]
	v_lshl_add_u64 v[74:75], v[92:93], 0, v[66:67]
	global_load_dwordx4 v[66:69], v[74:75], off offset:16
	global_load_dwordx4 v[70:73], v[74:75], off
.LBB0_2435:
	s_add_u32 s4, s4, s16
	s_addc_u32 s5, s5, s17
	v_mov_b64_e32 v[82:83], 0xaff
	v_cmp_gt_i64_e32 vcc, s[4:5], v[82:83]
	s_cbranch_vccnz .LBB0_2437
	s_ashr_i32 s9, s4, 31
	s_lshr_b32 s9, s9, 29
	s_add_i32 s9, s4, s9
	s_ashr_i32 s11, s9, 3
	s_and_b32 s9, s9, -8
	s_sub_i32 s9, s4, s9
	s_cmp_lt_i32 s9, 0
	s_movk_i32 s22, 0x161
	s_cselect_b32 s22, s22, 0x160
	s_mul_i32 s9, s22, s9
	s_add_i32 s9, s9, s11
	s_mul_hi_i32 s11, s9, 0x2e8ba2e9
	s_lshr_b32 s22, s11, 31
	s_ashr_i32 s11, s11, 5
	s_add_i32 s11, s11, s22
	s_lshl_b32 s22, s11, 3
	s_sub_i32 s23, 0x80, s22
	s_min_i32 s23, s23, 8
	s_mulk_i32 s11, 0xb0
	s_sub_i32 s9, s9, s11
	s_ashr_i32 s11, s9, 31
	s_abs_i32 s9, s9
	s_and_b32 s9, s9, 7
	s_add_i32 s9, s9, s22
	v_lshl_add_u32 v74, s9, 8, v91
	v_ashrrev_i32_e32 v75, 31, v74
	v_lshlrev_b64 v[74:75], 6, v[74:75]
	v_lshl_add_u64 v[84:85], v[92:93], 0, v[74:75]
	global_load_dwordx4 v[74:77], v[84:85], off offset:16
	global_load_dwordx4 v[78:81], v[84:85], off
.LBB0_2437:
	s_add_u32 s4, s4, s16
	s_addc_u32 s5, s5, s17
	v_cmp_gt_i64_e32 vcc, s[4:5], v[82:83]
	s_cbranch_vccnz .LBB0_2439
	s_ashr_i32 s9, s4, 31
	s_lshr_b32 s9, s9, 29
	s_add_i32 s9, s4, s9
	s_ashr_i32 s11, s9, 3
	s_and_b32 s9, s9, -8
	s_sub_i32 s9, s4, s9
	s_cmp_lt_i32 s9, 0
	s_movk_i32 s22, 0x161
	s_cselect_b32 s22, s22, 0x160
	s_mul_i32 s9, s22, s9
	s_add_i32 s9, s9, s11
	s_mul_hi_i32 s11, s9, 0x2e8ba2e9
	s_lshr_b32 s22, s11, 31
	s_ashr_i32 s11, s11, 5
	s_add_i32 s11, s11, s22
	s_lshl_b32 s22, s11, 3
	s_sub_i32 s23, 0x80, s22
	s_min_i32 s23, s23, 8
	s_mulk_i32 s11, 0xb0
	s_sub_i32 s9, s9, s11
	s_ashr_i32 s11, s9, 31
	s_abs_i32 s9, s9
	s_and_b32 s9, s9, 7
	s_add_i32 s9, s9, s22
	v_lshl_add_u32 v82, s9, 8, v91
	v_ashrrev_i32_e32 v83, 31, v82
	v_lshlrev_b64 v[82:83], 6, v[82:83]
	v_lshl_add_u64 v[94:95], v[92:93], 0, v[82:83]
	global_load_dwordx4 v[82:85], v[94:95], off offset:16
	global_load_dwordx4 v[86:89], v[94:95], off
.LBB0_2439:
	s_add_u32 s4, s4, s16
	s_addc_u32 s5, s5, s17
	v_mov_b64_e32 v[94:95], 0xaff
	v_cmp_gt_i64_e32 vcc, s[4:5], v[94:95]
	v_lshrrev_b32_e32 v99, 2, v0
	s_cbranch_vccnz .LBB0_2441
	s_ashr_i32 s5, s4, 31
	s_lshr_b32 s5, s5, 29
	s_add_i32 s5, s4, s5
	s_ashr_i32 s9, s5, 3
	s_and_b32 s5, s5, -8
	s_sub_i32 s4, s4, s5
	s_cmp_lt_i32 s4, 0
	s_movk_i32 s5, 0x161
	s_cselect_b32 s5, s5, 0x160
	s_mul_i32 s4, s5, s4
	s_add_i32 s4, s4, s9
	s_mul_hi_i32 s5, s4, 0x2e8ba2e9
	s_lshr_b32 s9, s5, 31
	s_ashr_i32 s5, s5, 5
	s_add_i32 s5, s5, s9
	s_lshl_b32 s9, s5, 3
	s_sub_i32 s11, 0x80, s9
	s_min_i32 s11, s11, 8
	s_mulk_i32 s5, 0xb0
	s_sub_i32 s4, s4, s5
	s_ashr_i32 s5, s4, 31
	s_abs_i32 s4, s4
	s_and_b32 s4, s4, 7
	s_add_i32 s4, s4, s9
	v_lshl_add_u32 v90, s4, 8, v91
	v_ashrrev_i32_e32 v91, 31, v90
	v_lshlrev_b64 v[90:91], 6, v[90:91]
	v_lshl_add_u64 v[100:101], v[92:93], 0, v[90:91]
	global_load_dwordx4 v[90:93], v[100:101], off offset:16
	global_load_dwordx4 v[94:97], v[100:101], off

; #define S xcd_barrier(bar);
;     __device__ bool next(int i, Unit& u) const {
;         const int ti = i / nsub; u.sub = i - ti * nsub;
;         const long L = (long)ti * G + c; if (L >= nwg) return false;
;         int wgid = (int)L; { const int q = nwg / NXCD, r = nwg % NXCD, xcd = wgid % NXCD, off = wgid / NXCD; wgid = (xcd < r ? xcd * (q + 1) : r * (q + 1) + (xcd - r) * q) + off; }
;         const int nig = WGM * nN, gid = wgid / nig, fm = gid * WGM, gsz = (nM - fm) < WGM ? (nM - fm) : WGM;
;         u.pm = fm + ((wgid % nig) % gsz); u.pn = (wgid % nig) / gsz; return true;
;     }
; template <class Epi, bool ALIGN_EPI, bool ABLK = false>
; __device__ __forceinline__ void gemm_phase(PG8_LAS unsigned char* lds, const Gemm g, const StaticOrder& S, const Epi& E) {
;     ...
;         const bool has_next = S.next(ui + 1, nxt);
;         const char* nA = has_next ? PG8_ABASE(nxt) : cA; const char* nB = has_next ? PG8_BBASE(nxt) : cB;
.LBB0_2492:
	s_add_i32 s78, s71, 1
	s_mul_i32 s5, s78, s16
	s_mul_hi_i32 s4, s78, s16
	s_add_u32 s54, s5, s2
	s_addc_u32 s55, s4, s65
	v_cmp_gt_i64_e64 s[4:5], s[54:55], v[156:157]
	v_cmp_lt_i64_e64 s[6:7], s[54:55], v[154:155]
	s_and_b64 vcc, exec, s[4:5]
	s_cbranch_vccnz .LBB0_2494
	s_ashr_i32 s50, s54, 31
	s_lshr_b32 s50, s50, 29
	s_add_i32 s50, s54, s50
	s_ashr_i32 s51, s50, 3
	s_and_b32 s50, s50, -8
	s_sub_i32 s50, s54, s50
	s_cmp_lt_i32 s50, 0
	s_movk_i32 s52, 0x161
	s_cselect_b32 s52, s52, 0x160
	s_mul_i32 s50, s52, s50
	s_add_i32 s50, s50, s51
	s_mul_hi_i32 s51, s50, 0x2e8ba2e9
	s_lshr_b32 s52, s51, 31
	s_ashr_i32 s51, s51, 5
	s_add_i32 s51, s51, s52
	s_lshl_b32 s52, s51, 3
	s_sub_i32 s53, 0x80, s52
	s_min_i32 s53, s53, 8
	s_mulk_i32 s51, 0xb0
	s_sub_i32 s51, s50, s51
	s_abs_i32 s50, s51
	s_ashr_i32 s50, s51, 3
	s_lshl_b32 s53, s50, 3
	s_and_b32 s51, s51, 7
	s_add_i32 s52, s51, s52

; #define S xcd_barrier(bar);
;     __device__ bool next(int i, Unit& u) const {
;         const int ti = i / nsub; u.sub = i - ti * nsub;
;         const long L = (long)ti * G + c; if (L >= nwg) return false;
;         int wgid = (int)L; { const int q = nwg / NXCD, r = nwg % NXCD, xcd = wgid % NXCD, off = wgid / NXCD; wgid = (xcd < r ? xcd * (q + 1) : r * (q + 1) + (xcd - r) * q) + off; }
;         const int nig = WGM * nN, gid = wgid / nig, fm = gid * WGM, gsz = (nM - fm) < WGM ? (nM - fm) : WGM;
;         u.pm = fm + ((wgid % nig) % gsz); u.pn = (wgid % nig) / gsz; return true;
;     }
; template <class Epi, bool ALIGN_EPI, bool ABLK = false>
; __device__ __forceinline__ void gemm_phase(PG8_LAS unsigned char* lds, const Gemm g, const StaticOrder& S, const Epi& E) {
;     ...
;         const bool has_next = S.next(ui + 1, nxt);
;         const char* nA = has_next ? PG8_ABASE(nxt) : cA; const char* nB = has_next ? PG8_BBASE(nxt) : cB;
.LBB0_2625:
	s_ashr_i32 s10, s48, 3
	s_add_i32 s10, s51, s10
	s_ashr_i32 s11, s10, 31
	s_lshr_b32 s11, s11, 27
	s_add_i32 s11, s10, s11
	s_ashr_i32 s48, s11, 5
	s_lshl_b32 s48, s48, 3
	s_sub_i32 s49, 0x80, s48
	s_min_i32 s49, s49, 8
	s_andn2_b32 s11, s11, 31
	s_sub_i32 s10, s10, s11
	s_abs_i32 s11, s10
	s_ashr_i32 s76, s10, 3
	s_lshl_b32 s11, s76, 3
	s_and_b32 s10, s10, 7
	s_add_i32 s77, s48, s10
